# row phases mode1/mode2 hand-scheduled: all row+param loads up front via SGPR bases, DPP row_bcast wave sums, params loaded once per wave
# speedup vs baseline: 1.0549x; 1.0130x over previous
.LBB0_49:
	s_add_i32 s0, s76, -2
	s_mul_hi_i32 s1, s0, 0x38e38e39
	s_lshr_b32 s4, s1, 31
	s_ashr_i32 s1, s1, 1
	s_add_i32 s6, s1, s4
	s_mul_i32 s1, s6, 9
	s_mov_b32 s4, s6
	s_sub_i32 s20, s0, s1
	v_writelane_b32 v254, s4, 34
	s_add_u32 s0, s84, 0xaeca000
	s_addc_u32 s1, s85, 0
	v_writelane_b32 v254, s5, 35
	v_writelane_b32 v254, s0, 36
	v_readfirstlane_b32 s28, v160
	s_nop 0
	v_writelane_b32 v254, s1, 37
	s_nop 0
	v_readlane_b32 s0, v254, 32
	v_readlane_b32 s1, v254, 33
	v_readlane_b32 s4, v254, 14
	s_lshl_b64 s[0:1], s[0:1], 2
	v_readlane_b32 s18, v254, 28
	v_readlane_b32 s5, v254, 15
	v_readlane_b32 s19, v254, 29
	s_add_u32 s4, s18, s0
	s_addc_u32 s5, s19, s1
	v_readlane_b32 s6, v254, 16
	v_readlane_b32 s7, v254, 17
	v_readlane_b32 s8, v254, 18
	v_readlane_b32 s9, v254, 19
	v_readlane_b32 s10, v254, 20
	v_readlane_b32 s11, v254, 21
	v_readlane_b32 s12, v254, 22
	v_readlane_b32 s13, v254, 23
	v_readlane_b32 s14, v254, 24
	v_readlane_b32 s15, v254, 25
	v_readlane_b32 s16, v254, 26
	v_readlane_b32 s17, v254, 27
	v_writelane_b32 v254, s4, 38
	s_cmp_lt_i32 s20, 4
	s_nop 0
	v_writelane_b32 v254, s5, 39
	v_writelane_b32 v254, s20, 40
	s_mov_b64 s[4:5], -1
	s_cbranch_scc1 .LBB0_214
	v_readlane_b32 s4, v254, 40
	s_cmp_lt_i32 s4, 6
	s_mov_b64 s[4:5], -1
	s_cbranch_scc1 .LBB0_168
	v_readlane_b32 s4, v254, 40
	s_cmp_lt_i32 s4, 7
	s_mov_b64 s[4:5], -1
	s_cbranch_scc1 .LBB0_150
	v_readlane_b32 s4, v254, 40
	s_cmp_lt_i32 s4, 8
	s_mov_b64 s[4:5], -1
	s_cbranch_scc1 .LBB0_101
	v_readlane_b32 s4, v254, 40
	s_cmp_eq_u32 s4, 8
	s_cbranch_scc0 .LBB0_100
	s_cmp_eq_u32 s76, 37
	s_cbranch_scc1 .Lrow2_last
	v_readfirstlane_b32 s0, v160
	v_readlane_b32 s1, v252, 7
	s_lshr_b32 s0, s0, 6
	s_add_i32 s0, s0, s1
	v_readlane_b32 s62, v254, 34
	s_sub_u32 s64, s78, 0x110
	s_subb_u32 s65, s79, 0
	s_load_dwordx2 s[66:67], s[64:65], 0x40
	s_load_dwordx2 s[10:11], s[64:65], 0xf8
	s_lshl_b32 s63, s0, 11
	s_add_u32 s4, s84, 0x167ca000
	s_addc_u32 s5, s85, 0
	s_add_u32 s4, s4, s63
	s_addc_u32 s5, s5, 0
	s_add_u32 s6, s84, 0x112ca000
	s_addc_u32 s7, s85, 0
	s_add_u32 s6, s6, s63
	s_addc_u32 s7, s7, 0
	v_and_b32_e32 v0, 63, v160
	v_lshlrev_b32_e32 v1, 4, v0
	v_lshlrev_b32_e32 v0, 3, v0
	v_add_u32_e32 v2, 0x400000, v0
	v_add_u32_e32 v3, 0x800000, v0
	v_add_u32_e32 v4, 0xc00000, v0
	v_add_u32_e32 v5, 0x1000000, v0
	global_load_dwordx2 v[8:9], v5, s[6:7] offset:0 nt
	global_load_dwordx2 v[10:11], v5, s[6:7] offset:512 nt
	global_load_dwordx2 v[12:13], v5, s[6:7] offset:1024 nt
	global_load_dwordx2 v[14:15], v5, s[6:7] offset:1536 nt
	global_load_dwordx2 v[16:17], v5, s[4:5] offset:0 nt
	global_load_dwordx2 v[18:19], v5, s[4:5] offset:512 nt
	global_load_dwordx2 v[20:21], v5, s[4:5] offset:1024 nt
	global_load_dwordx2 v[22:23], v5, s[4:5] offset:1536 nt
	s_add_u32 s8, s84, 0xaeca000
	s_addc_u32 s9, s85, 0
	s_add_u32 s8, s8, s63
	s_addc_u32 s9, s9, 0
	s_lshr_b32 s69, s0, 10
	s_add_i32 s69, s69, 1
	s_mul_i32 s69, s69, 0x6000
	s_mul_i32 s68, s62, 0x12000
	s_add_i32 s70, s62, 1
	s_mul_i32 s71, s70, 0x12000
	s_lshl_b32 s70, s70, 14
	s_lshl_b32 s72, s62, 14
	s_add_i32 s72, s72, 0x3000
	s_add_u32 s16, s84, 0x6605000
	s_addc_u32 s17, s85, 0
	s_add_u32 s16, s16, s68
	s_addc_u32 s17, s17, 0
	s_add_u32 s20, s84, 0x6600000
	s_addc_u32 s21, s85, 0
	s_add_u32 s20, s20, s71
	s_addc_u32 s21, s21, 0
	s_add_u32 s18, s20, 0x1000
	s_addc_u32 s19, s21, 0
	s_add_u32 s22, s16, s69
	s_addc_u32 s23, s17, 0
	s_add_u32 s60, s20, s69
	s_addc_u32 s61, s21, 0
	s_add_u32 s26, s18, s69
	s_addc_u32 s27, s19, 0
	s_lshl_b32 s63, s63, 1
	s_waitcnt lgkmcnt(0)
	s_add_u32 s12, s66, s72
	s_addc_u32 s13, s67, 0
	s_add_u32 s14, s66, s70
	s_addc_u32 s15, s67, 0
	s_add_u32 s10, s10, s63
	s_addc_u32 s11, s11, 0
	global_load_dwordx4 v[190:193], v1, s[22:23] offset:0
	global_load_dwordx4 v[194:197], v1, s[22:23] offset:1024
	global_load_dwordx4 v[198:201], v1, s[22:23] offset:2048
	global_load_dwordx4 v[202:205], v1, s[22:23] offset:3072
	global_load_dwordx4 v[56:59], v1, s[12:13] offset:0
	global_load_dwordx4 v[60:63], v1, s[12:13] offset:1024
	global_load_dwordx4 v[64:67], v1, s[12:13] offset:2048
	global_load_dwordx4 v[68:71], v1, s[12:13] offset:3072
	global_load_dwordx4 v[72:75], v1, s[14:15] offset:0
	global_load_dwordx4 v[76:79], v1, s[14:15] offset:1024
	global_load_dwordx4 v[80:83], v1, s[14:15] offset:2048
	global_load_dwordx4 v[84:87], v1, s[14:15] offset:3072
	global_load_dwordx4 v[206:209], v1, s[26:27] offset:0
	global_load_dwordx4 v[210:213], v1, s[26:27] offset:1024
	global_load_dwordx4 v[214:217], v1, s[26:27] offset:2048
	global_load_dwordx4 v[218:221], v1, s[26:27] offset:3072
	global_load_dwordx4 v[222:225], v1, s[60:61] offset:0
	global_load_dwordx4 v[226:229], v1, s[60:61] offset:1024
	global_load_dwordx4 v[230:233], v1, s[60:61] offset:2048
	global_load_dwordx4 v[234:237], v1, s[60:61] offset:3072
	global_load_dwordx2 v[24:25], v0, s[6:7] offset:0 nt
	global_load_dwordx2 v[26:27], v0, s[6:7] offset:512 nt
	global_load_dwordx2 v[28:29], v0, s[6:7] offset:1024 nt
	global_load_dwordx2 v[30:31], v0, s[6:7] offset:1536 nt
	global_load_dwordx2 v[32:33], v0, s[4:5] offset:0 nt
	global_load_dwordx2 v[34:35], v0, s[4:5] offset:512 nt
	global_load_dwordx2 v[36:37], v0, s[4:5] offset:1024 nt
	global_load_dwordx2 v[38:39], v0, s[4:5] offset:1536 nt
	global_load_dwordx4 v[88:91], v1, s[16:17] offset:0
	global_load_dwordx4 v[92:95], v1, s[16:17] offset:1024
	global_load_dwordx4 v[96:99], v1, s[16:17] offset:2048
	global_load_dwordx4 v[100:103], v1, s[16:17] offset:3072
	global_load_dwordx4 v[104:107], v1, s[18:19] offset:0
	global_load_dwordx4 v[108:111], v1, s[18:19] offset:1024
	global_load_dwordx4 v[112:115], v1, s[18:19] offset:2048
	global_load_dwordx4 v[116:119], v1, s[18:19] offset:3072
	global_load_dwordx4 v[134:137], v1, s[20:21] offset:0
	global_load_dwordx4 v[138:141], v1, s[20:21] offset:1024
	global_load_dwordx4 v[142:145], v1, s[20:21] offset:2048
	global_load_dwordx4 v[146:149], v1, s[20:21] offset:3072
	global_load_dwordx2 v[40:41], v2, s[6:7] offset:0 nt
	global_load_dwordx2 v[42:43], v2, s[6:7] offset:512 nt
	global_load_dwordx2 v[44:45], v2, s[6:7] offset:1024 nt
	global_load_dwordx2 v[46:47], v2, s[6:7] offset:1536 nt
	global_load_dwordx2 v[48:49], v2, s[4:5] offset:0 nt
	global_load_dwordx2 v[50:51], v2, s[4:5] offset:512 nt
	global_load_dwordx2 v[52:53], v2, s[4:5] offset:1024 nt
	global_load_dwordx2 v[54:55], v2, s[4:5] offset:1536 nt
	s_waitcnt vmcnt(52)
	v_lshlrev_b32_e32 v246, 16, v8
	v_and_b32_e32 v8, 0xffff0000, v8
	v_lshlrev_b32_e32 v247, 16, v9
	v_and_b32_e32 v9, 0xffff0000, v9
	v_lshlrev_b32_e32 v248, 16, v10
	v_and_b32_e32 v10, 0xffff0000, v10
	v_lshlrev_b32_e32 v249, 16, v11
	v_and_b32_e32 v11, 0xffff0000, v11
	v_lshlrev_b32_e32 v250, 16, v12
	v_and_b32_e32 v12, 0xffff0000, v12
	v_lshlrev_b32_e32 v251, 16, v13
	v_and_b32_e32 v13, 0xffff0000, v13
	v_lshlrev_b32_e32 v176, 16, v14
	v_and_b32_e32 v14, 0xffff0000, v14
	v_lshlrev_b32_e32 v177, 16, v15
	v_and_b32_e32 v15, 0xffff0000, v15
	v_mul_f32_e32 v178, v246, v246
	v_fmac_f32_e32 v178, v8, v8
	v_fmac_f32_e32 v178, v247, v247
	v_fmac_f32_e32 v178, v9, v9
	v_fmac_f32_e32 v178, v248, v248
	v_fmac_f32_e32 v178, v10, v10
	v_fmac_f32_e32 v178, v249, v249
	v_fmac_f32_e32 v178, v11, v11
	v_fmac_f32_e32 v178, v250, v250
	v_fmac_f32_e32 v178, v12, v12
	v_fmac_f32_e32 v178, v251, v251
	v_fmac_f32_e32 v178, v13, v13
	v_fmac_f32_e32 v178, v176, v176
	v_fmac_f32_e32 v178, v14, v14
	v_fmac_f32_e32 v178, v177, v177
	v_fmac_f32_e32 v178, v15, v15
	s_waitcnt vmcnt(48)
	v_lshlrev_b32_e32 v238, 16, v16
	v_and_b32_e32 v16, 0xffff0000, v16
	v_add_f32_dpp v178, v178, v178 quad_perm:[1,0,3,2] row_mask:0xf bank_mask:0xf bound_ctrl:1
	v_lshlrev_b32_e32 v239, 16, v17
	v_and_b32_e32 v17, 0xffff0000, v17
	v_add_f32_dpp v178, v178, v178 quad_perm:[2,3,0,1] row_mask:0xf bank_mask:0xf bound_ctrl:1
	v_lshlrev_b32_e32 v240, 16, v18
	v_and_b32_e32 v18, 0xffff0000, v18
	v_add_f32_dpp v178, v178, v178 row_half_mirror row_mask:0xf bank_mask:0xf bound_ctrl:1
	v_lshlrev_b32_e32 v241, 16, v19
	v_and_b32_e32 v19, 0xffff0000, v19
	v_add_f32_dpp v178, v178, v178 row_mirror row_mask:0xf bank_mask:0xf bound_ctrl:1
	v_lshlrev_b32_e32 v242, 16, v20
	v_and_b32_e32 v20, 0xffff0000, v20
	v_add_f32_dpp v178, v178, v178 row_bcast:15 row_mask:0xa bank_mask:0xf
	v_lshlrev_b32_e32 v243, 16, v21
	v_and_b32_e32 v21, 0xffff0000, v21
	v_add_f32_dpp v178, v178, v178 row_bcast:31 row_mask:0xc bank_mask:0xf
	v_lshlrev_b32_e32 v244, 16, v22
	v_and_b32_e32 v22, 0xffff0000, v22
	v_lshlrev_b32_e32 v245, 16, v23
	v_and_b32_e32 v23, 0xffff0000, v23
	v_readlane_b32 s0, v178, 63
	s_nop 1
	v_mov_b32_e32 v181, s0
	v_fmamk_f32 v181, v181, 0x3a800000, v161
	v_rsq_f32_e32 v179, v181
	s_nop 0
	s_waitcnt vmcnt(40)
	v_mul_f32_e32 v246, v246, v179
	v_mul_f32_e32 v8, v8, v179
	v_mul_f32_e32 v247, v247, v179
	v_mul_f32_e32 v9, v9, v179
	v_mul_f32_e32 v248, v248, v179
	v_mul_f32_e32 v10, v10, v179
	v_mul_f32_e32 v249, v249, v179
	v_mul_f32_e32 v11, v11, v179
	v_mul_f32_e32 v250, v250, v179
	v_mul_f32_e32 v12, v12, v179
	v_mul_f32_e32 v251, v251, v179
	v_mul_f32_e32 v13, v13, v179
	v_mul_f32_e32 v176, v176, v179
	v_mul_f32_e32 v14, v14, v179
	v_mul_f32_e32 v177, v177, v179
	v_mul_f32_e32 v15, v15, v179
	v_mul_f32_e32 v246, v246, v56
	v_mul_f32_e32 v8, v8, v57
	v_mul_f32_e32 v247, v247, v58
	v_mul_f32_e32 v9, v9, v59
	v_mul_f32_e32 v248, v248, v60
	v_mul_f32_e32 v10, v10, v61
	v_mul_f32_e32 v249, v249, v62
	v_mul_f32_e32 v11, v11, v63
	v_mul_f32_e32 v250, v250, v64
	v_mul_f32_e32 v12, v12, v65
	v_mul_f32_e32 v251, v251, v66
	v_mul_f32_e32 v13, v13, v67
	v_mul_f32_e32 v176, v176, v68
	v_mul_f32_e32 v14, v14, v69
	v_mul_f32_e32 v177, v177, v70
	v_mul_f32_e32 v15, v15, v71
	v_fmac_f32_e32 v238, v190, v246
	v_fmac_f32_e32 v16, v191, v8
	v_fmac_f32_e32 v239, v192, v247
	v_fmac_f32_e32 v17, v193, v9
	v_fmac_f32_e32 v240, v194, v248
	v_fmac_f32_e32 v18, v195, v10
	v_fmac_f32_e32 v241, v196, v249
	v_fmac_f32_e32 v19, v197, v11
	v_fmac_f32_e32 v242, v198, v250
	v_fmac_f32_e32 v20, v199, v12
	v_fmac_f32_e32 v243, v200, v251
	v_fmac_f32_e32 v21, v201, v13
	v_fmac_f32_e32 v244, v202, v176
	v_fmac_f32_e32 v22, v203, v14
	v_fmac_f32_e32 v245, v204, v177
	v_fmac_f32_e32 v23, v205, v15
	v_cvt_pk_bf16_f32 v120, v238, v16
	v_cvt_pk_bf16_f32 v121, v239, v17
	global_store_dwordx2 v5, v[120:121], s[4:5] offset:0 nt
	v_cvt_pk_bf16_f32 v122, v240, v18
	v_cvt_pk_bf16_f32 v123, v241, v19
	global_store_dwordx2 v5, v[122:123], s[4:5] offset:512 nt
	v_cvt_pk_bf16_f32 v124, v242, v20
	v_cvt_pk_bf16_f32 v125, v243, v21
	global_store_dwordx2 v5, v[124:125], s[4:5] offset:1024 nt
	v_cvt_pk_bf16_f32 v126, v244, v22
	v_cvt_pk_bf16_f32 v127, v245, v23
	global_store_dwordx2 v5, v[126:127], s[4:5] offset:1536 nt
	v_mul_f32_e32 v178, v238, v238
	v_fmac_f32_e32 v178, v16, v16
	v_fmac_f32_e32 v178, v239, v239
	v_fmac_f32_e32 v178, v17, v17
	v_fmac_f32_e32 v178, v240, v240
	v_fmac_f32_e32 v178, v18, v18
	v_fmac_f32_e32 v178, v241, v241
	v_fmac_f32_e32 v178, v19, v19
	v_fmac_f32_e32 v178, v242, v242
	v_fmac_f32_e32 v178, v20, v20
	v_fmac_f32_e32 v178, v243, v243
	v_fmac_f32_e32 v178, v21, v21
	v_fmac_f32_e32 v178, v244, v244
	v_fmac_f32_e32 v178, v22, v22
	v_fmac_f32_e32 v178, v245, v245
	v_fmac_f32_e32 v178, v23, v23
	s_waitcnt vmcnt(36)
	v_add_f32_e32 v206, 1.0, v206
	v_add_f32_e32 v207, 1.0, v207
	v_add_f32_dpp v178, v178, v178 quad_perm:[1,0,3,2] row_mask:0xf bank_mask:0xf bound_ctrl:1
	v_add_f32_e32 v208, 1.0, v208
	v_add_f32_e32 v209, 1.0, v209
	v_add_f32_dpp v178, v178, v178 quad_perm:[2,3,0,1] row_mask:0xf bank_mask:0xf bound_ctrl:1
	v_add_f32_e32 v210, 1.0, v210
	v_add_f32_e32 v211, 1.0, v211
	v_add_f32_dpp v178, v178, v178 row_half_mirror row_mask:0xf bank_mask:0xf bound_ctrl:1
	v_add_f32_e32 v212, 1.0, v212
	v_add_f32_e32 v213, 1.0, v213
	v_add_f32_dpp v178, v178, v178 row_mirror row_mask:0xf bank_mask:0xf bound_ctrl:1
	v_add_f32_e32 v214, 1.0, v214
	v_add_f32_e32 v215, 1.0, v215
	v_add_f32_dpp v178, v178, v178 row_bcast:15 row_mask:0xa bank_mask:0xf
	v_add_f32_e32 v216, 1.0, v216
	v_add_f32_e32 v217, 1.0, v217
	v_add_f32_dpp v178, v178, v178 row_bcast:31 row_mask:0xc bank_mask:0xf
	v_add_f32_e32 v218, 1.0, v218
	v_add_f32_e32 v219, 1.0, v219
	v_add_f32_e32 v220, 1.0, v220
	v_add_f32_e32 v221, 1.0, v221
	v_readlane_b32 s0, v178, 63
	s_nop 1
	v_mov_b32_e32 v181, s0
	v_fmamk_f32 v181, v181, 0x3a800000, v161
	v_rsq_f32_e32 v180, v181
	s_nop 0
	s_waitcnt vmcnt(32)
	v_mul_f32_e32 v238, v238, v180
	v_mul_f32_e32 v16, v16, v180
	v_mul_f32_e32 v239, v239, v180
	v_mul_f32_e32 v17, v17, v180
	v_mul_f32_e32 v240, v240, v180
	v_mul_f32_e32 v18, v18, v180
	v_mul_f32_e32 v241, v241, v180
	v_mul_f32_e32 v19, v19, v180
	v_mul_f32_e32 v242, v242, v180
	v_mul_f32_e32 v20, v20, v180
	v_mul_f32_e32 v243, v243, v180
	v_mul_f32_e32 v21, v21, v180
	v_mul_f32_e32 v244, v244, v180
	v_mul_f32_e32 v22, v22, v180
	v_mul_f32_e32 v245, v245, v180
	v_mul_f32_e32 v23, v23, v180
	v_mul_f32_e32 v238, v238, v72
	v_mul_f32_e32 v16, v16, v73
	v_mul_f32_e32 v239, v239, v74
	v_mul_f32_e32 v17, v17, v75
	v_mul_f32_e32 v240, v240, v76
	v_mul_f32_e32 v18, v18, v77
	v_mul_f32_e32 v241, v241, v78
	v_mul_f32_e32 v19, v19, v79
	v_mul_f32_e32 v242, v242, v80
	v_mul_f32_e32 v20, v20, v81
	v_mul_f32_e32 v243, v243, v82
	v_mul_f32_e32 v21, v21, v83
	v_mul_f32_e32 v244, v244, v84
	v_mul_f32_e32 v22, v22, v85
	v_mul_f32_e32 v245, v245, v86
	v_mul_f32_e32 v23, v23, v87
	v_fma_f32 v238, v238, v206, v222
	v_fma_f32 v16, v16, v207, v223
	v_fma_f32 v239, v239, v208, v224
	v_fma_f32 v17, v17, v209, v225
	v_fma_f32 v240, v240, v210, v226
	v_fma_f32 v18, v18, v211, v227
	v_fma_f32 v241, v241, v212, v228
	v_fma_f32 v19, v19, v213, v229
	v_fma_f32 v242, v242, v214, v230
	v_fma_f32 v20, v20, v215, v231
	v_fma_f32 v243, v243, v216, v232
	v_fma_f32 v21, v21, v217, v233
	v_fma_f32 v244, v244, v218, v234
	v_fma_f32 v22, v22, v219, v235
	v_fma_f32 v245, v245, v220, v236
	v_fma_f32 v23, v23, v221, v237
	v_cvt_pk_bf16_f32 v150, v238, v16
	v_cvt_pk_bf16_f32 v151, v239, v17
	global_store_dwordx2 v5, v[150:151], s[8:9] offset:0
	v_cvt_pk_bf16_f32 v152, v240, v18
	v_cvt_pk_bf16_f32 v153, v241, v19
	global_store_dwordx2 v5, v[152:153], s[8:9] offset:512
	v_cvt_pk_bf16_f32 v154, v242, v20
	v_cvt_pk_bf16_f32 v155, v243, v21
	global_store_dwordx2 v5, v[154:155], s[8:9] offset:1024
	v_cvt_pk_bf16_f32 v156, v244, v22
	v_cvt_pk_bf16_f32 v157, v245, v23
	global_store_dwordx2 v5, v[156:157], s[8:9] offset:1536
	global_load_dwordx2 v[8:9], v3, s[6:7] offset:0 nt
	global_load_dwordx2 v[10:11], v3, s[6:7] offset:512 nt
	global_load_dwordx2 v[12:13], v3, s[6:7] offset:1024 nt
	global_load_dwordx2 v[14:15], v3, s[6:7] offset:1536 nt
	global_load_dwordx2 v[16:17], v3, s[4:5] offset:0 nt
	global_load_dwordx2 v[18:19], v3, s[4:5] offset:512 nt
	global_load_dwordx2 v[20:21], v3, s[4:5] offset:1024 nt
	global_load_dwordx2 v[22:23], v3, s[4:5] offset:1536 nt
	global_load_dwordx2 v[190:191], v4, s[6:7] offset:0 nt
	global_load_dwordx2 v[192:193], v4, s[6:7] offset:512 nt
	global_load_dwordx2 v[194:195], v4, s[6:7] offset:1024 nt
	global_load_dwordx2 v[196:197], v4, s[6:7] offset:1536 nt
	global_load_dwordx2 v[198:199], v4, s[4:5] offset:0 nt
	global_load_dwordx2 v[200:201], v4, s[4:5] offset:512 nt
	global_load_dwordx2 v[202:203], v4, s[4:5] offset:1024 nt
	global_load_dwordx2 v[204:205], v4, s[4:5] offset:1536 nt
	s_waitcnt vmcnt(48)
	v_lshlrev_b32_e32 v246, 16, v24
	v_and_b32_e32 v24, 0xffff0000, v24
	v_lshlrev_b32_e32 v247, 16, v25
	v_and_b32_e32 v25, 0xffff0000, v25
	v_lshlrev_b32_e32 v248, 16, v26
	v_and_b32_e32 v26, 0xffff0000, v26
	v_lshlrev_b32_e32 v249, 16, v27
	v_and_b32_e32 v27, 0xffff0000, v27
	v_lshlrev_b32_e32 v250, 16, v28
	v_and_b32_e32 v28, 0xffff0000, v28
	v_lshlrev_b32_e32 v251, 16, v29
	v_and_b32_e32 v29, 0xffff0000, v29
	v_lshlrev_b32_e32 v176, 16, v30
	v_and_b32_e32 v30, 0xffff0000, v30
	v_lshlrev_b32_e32 v177, 16, v31
	v_and_b32_e32 v31, 0xffff0000, v31
	v_mul_f32_e32 v178, v246, v246
	v_fmac_f32_e32 v178, v24, v24
	v_fmac_f32_e32 v178, v247, v247
	v_fmac_f32_e32 v178, v25, v25
	v_fmac_f32_e32 v178, v248, v248
	v_fmac_f32_e32 v178, v26, v26
	v_fmac_f32_e32 v178, v249, v249
	v_fmac_f32_e32 v178, v27, v27
	v_fmac_f32_e32 v178, v250, v250
	v_fmac_f32_e32 v178, v28, v28
	v_fmac_f32_e32 v178, v251, v251
	v_fmac_f32_e32 v178, v29, v29
	v_fmac_f32_e32 v178, v176, v176
	v_fmac_f32_e32 v178, v30, v30
	v_fmac_f32_e32 v178, v177, v177
	v_fmac_f32_e32 v178, v31, v31
	s_waitcnt vmcnt(44)
	v_lshlrev_b32_e32 v238, 16, v32
	v_and_b32_e32 v32, 0xffff0000, v32
	v_add_f32_dpp v178, v178, v178 quad_perm:[1,0,3,2] row_mask:0xf bank_mask:0xf bound_ctrl:1
	v_lshlrev_b32_e32 v239, 16, v33
	v_and_b32_e32 v33, 0xffff0000, v33
	v_add_f32_dpp v178, v178, v178 quad_perm:[2,3,0,1] row_mask:0xf bank_mask:0xf bound_ctrl:1
	v_lshlrev_b32_e32 v240, 16, v34
	v_and_b32_e32 v34, 0xffff0000, v34
	v_add_f32_dpp v178, v178, v178 row_half_mirror row_mask:0xf bank_mask:0xf bound_ctrl:1
	v_lshlrev_b32_e32 v241, 16, v35
	v_and_b32_e32 v35, 0xffff0000, v35
	v_add_f32_dpp v178, v178, v178 row_mirror row_mask:0xf bank_mask:0xf bound_ctrl:1
	v_lshlrev_b32_e32 v242, 16, v36
	v_and_b32_e32 v36, 0xffff0000, v36
	v_add_f32_dpp v178, v178, v178 row_bcast:15 row_mask:0xa bank_mask:0xf
	v_lshlrev_b32_e32 v243, 16, v37
	v_and_b32_e32 v37, 0xffff0000, v37
	v_add_f32_dpp v178, v178, v178 row_bcast:31 row_mask:0xc bank_mask:0xf
	v_lshlrev_b32_e32 v244, 16, v38
	v_and_b32_e32 v38, 0xffff0000, v38
	v_lshlrev_b32_e32 v245, 16, v39
	v_and_b32_e32 v39, 0xffff0000, v39
	v_readlane_b32 s0, v178, 63
	s_nop 1
	v_mov_b32_e32 v181, s0
	v_fmamk_f32 v181, v181, 0x3a800000, v161
	v_rsq_f32_e32 v179, v181
	s_nop 0
	s_waitcnt vmcnt(40)
	v_mul_f32_e32 v246, v246, v179
	v_mul_f32_e32 v24, v24, v179
	v_mul_f32_e32 v247, v247, v179
	v_mul_f32_e32 v25, v25, v179
	v_mul_f32_e32 v248, v248, v179
	v_mul_f32_e32 v26, v26, v179
	v_mul_f32_e32 v249, v249, v179
	v_mul_f32_e32 v27, v27, v179
	v_mul_f32_e32 v250, v250, v179
	v_mul_f32_e32 v28, v28, v179
	v_mul_f32_e32 v251, v251, v179
	v_mul_f32_e32 v29, v29, v179
	v_mul_f32_e32 v176, v176, v179
	v_mul_f32_e32 v30, v30, v179
	v_mul_f32_e32 v177, v177, v179
	v_mul_f32_e32 v31, v31, v179
	v_mul_f32_e32 v246, v246, v56
	v_mul_f32_e32 v24, v24, v57
	v_mul_f32_e32 v247, v247, v58
	v_mul_f32_e32 v25, v25, v59
	v_mul_f32_e32 v248, v248, v60
	v_mul_f32_e32 v26, v26, v61
	v_mul_f32_e32 v249, v249, v62
	v_mul_f32_e32 v27, v27, v63
	v_mul_f32_e32 v250, v250, v64
	v_mul_f32_e32 v28, v28, v65
	v_mul_f32_e32 v251, v251, v66
	v_mul_f32_e32 v29, v29, v67
	v_mul_f32_e32 v176, v176, v68
	v_mul_f32_e32 v30, v30, v69
	v_mul_f32_e32 v177, v177, v70
	v_mul_f32_e32 v31, v31, v71
	v_fmac_f32_e32 v238, v88, v246
	v_fmac_f32_e32 v32, v89, v24
	v_fmac_f32_e32 v239, v90, v247
	v_fmac_f32_e32 v33, v91, v25
	v_fmac_f32_e32 v240, v92, v248
	v_fmac_f32_e32 v34, v93, v26
	v_fmac_f32_e32 v241, v94, v249
	v_fmac_f32_e32 v35, v95, v27
	v_fmac_f32_e32 v242, v96, v250
	v_fmac_f32_e32 v36, v97, v28
	v_fmac_f32_e32 v243, v98, v251
	v_fmac_f32_e32 v37, v99, v29
	v_fmac_f32_e32 v244, v100, v176
	v_fmac_f32_e32 v38, v101, v30
	v_fmac_f32_e32 v245, v102, v177
	v_fmac_f32_e32 v39, v103, v31
	v_cvt_pk_bf16_f32 v120, v238, v32
	v_cvt_pk_bf16_f32 v121, v239, v33
	global_store_dwordx2 v0, v[120:121], s[4:5] offset:0 nt
	v_cvt_pk_bf16_f32 v122, v240, v34
	v_cvt_pk_bf16_f32 v123, v241, v35
	global_store_dwordx2 v0, v[122:123], s[4:5] offset:512 nt
	v_cvt_pk_bf16_f32 v124, v242, v36
	v_cvt_pk_bf16_f32 v125, v243, v37
	global_store_dwordx2 v0, v[124:125], s[4:5] offset:1024 nt
	v_cvt_pk_bf16_f32 v126, v244, v38
	v_cvt_pk_bf16_f32 v127, v245, v39
	global_store_dwordx2 v0, v[126:127], s[4:5] offset:1536 nt
	v_mul_f32_e32 v178, v238, v238
	v_fmac_f32_e32 v178, v32, v32
	v_fmac_f32_e32 v178, v239, v239
	v_fmac_f32_e32 v178, v33, v33
	v_fmac_f32_e32 v178, v240, v240
	v_fmac_f32_e32 v178, v34, v34
	v_fmac_f32_e32 v178, v241, v241
	v_fmac_f32_e32 v178, v35, v35
	v_fmac_f32_e32 v178, v242, v242
	v_fmac_f32_e32 v178, v36, v36
	v_fmac_f32_e32 v178, v243, v243
	v_fmac_f32_e32 v178, v37, v37
	v_fmac_f32_e32 v178, v244, v244
	v_fmac_f32_e32 v178, v38, v38
	v_fmac_f32_e32 v178, v245, v245
	v_fmac_f32_e32 v178, v39, v39
	s_waitcnt vmcnt(40)
	v_add_f32_e32 v104, 1.0, v104
	v_add_f32_e32 v105, 1.0, v105
	v_add_f32_dpp v178, v178, v178 quad_perm:[1,0,3,2] row_mask:0xf bank_mask:0xf bound_ctrl:1
	v_add_f32_e32 v106, 1.0, v106
	v_add_f32_e32 v107, 1.0, v107
	v_add_f32_dpp v178, v178, v178 quad_perm:[2,3,0,1] row_mask:0xf bank_mask:0xf bound_ctrl:1
	v_add_f32_e32 v108, 1.0, v108
	v_add_f32_e32 v109, 1.0, v109
	v_add_f32_dpp v178, v178, v178 row_half_mirror row_mask:0xf bank_mask:0xf bound_ctrl:1
	v_add_f32_e32 v110, 1.0, v110
	v_add_f32_e32 v111, 1.0, v111
	v_add_f32_dpp v178, v178, v178 row_mirror row_mask:0xf bank_mask:0xf bound_ctrl:1
	v_add_f32_e32 v112, 1.0, v112
	v_add_f32_e32 v113, 1.0, v113
	v_add_f32_dpp v178, v178, v178 row_bcast:15 row_mask:0xa bank_mask:0xf
	v_add_f32_e32 v114, 1.0, v114
	v_add_f32_e32 v115, 1.0, v115
	v_add_f32_dpp v178, v178, v178 row_bcast:31 row_mask:0xc bank_mask:0xf
	v_add_f32_e32 v116, 1.0, v116
	v_add_f32_e32 v117, 1.0, v117
	v_add_f32_e32 v118, 1.0, v118
	v_add_f32_e32 v119, 1.0, v119
	v_readlane_b32 s0, v178, 63
	s_nop 1
	v_mov_b32_e32 v181, s0
	v_fmamk_f32 v181, v181, 0x3a800000, v161
	v_rsq_f32_e32 v180, v181
	s_nop 0
	s_waitcnt vmcnt(36)
	v_mul_f32_e32 v238, v238, v180
	v_mul_f32_e32 v32, v32, v180
	v_mul_f32_e32 v239, v239, v180
	v_mul_f32_e32 v33, v33, v180
	v_mul_f32_e32 v240, v240, v180
	v_mul_f32_e32 v34, v34, v180
	v_mul_f32_e32 v241, v241, v180
	v_mul_f32_e32 v35, v35, v180
	v_mul_f32_e32 v242, v242, v180
	v_mul_f32_e32 v36, v36, v180
	v_mul_f32_e32 v243, v243, v180
	v_mul_f32_e32 v37, v37, v180
	v_mul_f32_e32 v244, v244, v180
	v_mul_f32_e32 v38, v38, v180
	v_mul_f32_e32 v245, v245, v180
	v_mul_f32_e32 v39, v39, v180
	v_mul_f32_e32 v238, v238, v72
	v_mul_f32_e32 v32, v32, v73
	v_mul_f32_e32 v239, v239, v74
	v_mul_f32_e32 v33, v33, v75
	v_mul_f32_e32 v240, v240, v76
	v_mul_f32_e32 v34, v34, v77
	v_mul_f32_e32 v241, v241, v78
	v_mul_f32_e32 v35, v35, v79
	v_mul_f32_e32 v242, v242, v80
	v_mul_f32_e32 v36, v36, v81
	v_mul_f32_e32 v243, v243, v82
	v_mul_f32_e32 v37, v37, v83
	v_mul_f32_e32 v244, v244, v84
	v_mul_f32_e32 v38, v38, v85
	v_mul_f32_e32 v245, v245, v86
	v_mul_f32_e32 v39, v39, v87
	v_fma_f32 v238, v238, v104, v134
	v_fma_f32 v32, v32, v105, v135
	v_fma_f32 v239, v239, v106, v136
	v_fma_f32 v33, v33, v107, v137
	v_fma_f32 v240, v240, v108, v138
	v_fma_f32 v34, v34, v109, v139
	v_fma_f32 v241, v241, v110, v140
	v_fma_f32 v35, v35, v111, v141
	v_fma_f32 v242, v242, v112, v142
	v_fma_f32 v36, v36, v113, v143
	v_fma_f32 v243, v243, v114, v144
	v_fma_f32 v37, v37, v115, v145
	v_fma_f32 v244, v244, v116, v146
	v_fma_f32 v38, v38, v117, v147
	v_fma_f32 v245, v245, v118, v148
	v_fma_f32 v39, v39, v119, v149
	v_cvt_pk_bf16_f32 v150, v238, v32
	v_cvt_pk_bf16_f32 v151, v239, v33
	global_store_dwordx2 v0, v[150:151], s[8:9] offset:0
	v_cvt_pk_bf16_f32 v152, v240, v34
	v_cvt_pk_bf16_f32 v153, v241, v35
	global_store_dwordx2 v0, v[152:153], s[8:9] offset:512
	v_cvt_pk_bf16_f32 v154, v242, v36
	v_cvt_pk_bf16_f32 v155, v243, v37
	global_store_dwordx2 v0, v[154:155], s[8:9] offset:1024
	v_cvt_pk_bf16_f32 v156, v244, v38
	v_cvt_pk_bf16_f32 v157, v245, v39
	global_store_dwordx2 v0, v[156:157], s[8:9] offset:1536
	s_waitcnt vmcnt(36)
	v_lshlrev_b32_e32 v246, 16, v40
	v_and_b32_e32 v40, 0xffff0000, v40
	v_lshlrev_b32_e32 v247, 16, v41
	v_and_b32_e32 v41, 0xffff0000, v41
	v_lshlrev_b32_e32 v248, 16, v42
	v_and_b32_e32 v42, 0xffff0000, v42
	v_lshlrev_b32_e32 v249, 16, v43
	v_and_b32_e32 v43, 0xffff0000, v43
	v_lshlrev_b32_e32 v250, 16, v44
	v_and_b32_e32 v44, 0xffff0000, v44
	v_lshlrev_b32_e32 v251, 16, v45
	v_and_b32_e32 v45, 0xffff0000, v45
	v_lshlrev_b32_e32 v176, 16, v46
	v_and_b32_e32 v46, 0xffff0000, v46
	v_lshlrev_b32_e32 v177, 16, v47
	v_and_b32_e32 v47, 0xffff0000, v47
	v_mul_f32_e32 v178, v246, v246
	v_fmac_f32_e32 v178, v40, v40
	v_fmac_f32_e32 v178, v247, v247
	v_fmac_f32_e32 v178, v41, v41
	v_fmac_f32_e32 v178, v248, v248
	v_fmac_f32_e32 v178, v42, v42
	v_fmac_f32_e32 v178, v249, v249
	v_fmac_f32_e32 v178, v43, v43
	v_fmac_f32_e32 v178, v250, v250
	v_fmac_f32_e32 v178, v44, v44
	v_fmac_f32_e32 v178, v251, v251
	v_fmac_f32_e32 v178, v45, v45
	v_fmac_f32_e32 v178, v176, v176
	v_fmac_f32_e32 v178, v46, v46
	v_fmac_f32_e32 v178, v177, v177
	v_fmac_f32_e32 v178, v47, v47
	s_waitcnt vmcnt(32)
	v_lshlrev_b32_e32 v238, 16, v48
	v_and_b32_e32 v48, 0xffff0000, v48
	v_add_f32_dpp v178, v178, v178 quad_perm:[1,0,3,2] row_mask:0xf bank_mask:0xf bound_ctrl:1
	v_lshlrev_b32_e32 v239, 16, v49
	v_and_b32_e32 v49, 0xffff0000, v49
	v_add_f32_dpp v178, v178, v178 quad_perm:[2,3,0,1] row_mask:0xf bank_mask:0xf bound_ctrl:1
	v_lshlrev_b32_e32 v240, 16, v50
	v_and_b32_e32 v50, 0xffff0000, v50
	v_add_f32_dpp v178, v178, v178 row_half_mirror row_mask:0xf bank_mask:0xf bound_ctrl:1
	v_lshlrev_b32_e32 v241, 16, v51
	v_and_b32_e32 v51, 0xffff0000, v51
	v_add_f32_dpp v178, v178, v178 row_mirror row_mask:0xf bank_mask:0xf bound_ctrl:1
	v_lshlrev_b32_e32 v242, 16, v52
	v_and_b32_e32 v52, 0xffff0000, v52
	v_add_f32_dpp v178, v178, v178 row_bcast:15 row_mask:0xa bank_mask:0xf
	v_lshlrev_b32_e32 v243, 16, v53
	v_and_b32_e32 v53, 0xffff0000, v53
	v_add_f32_dpp v178, v178, v178 row_bcast:31 row_mask:0xc bank_mask:0xf
	v_lshlrev_b32_e32 v244, 16, v54
	v_and_b32_e32 v54, 0xffff0000, v54
	v_lshlrev_b32_e32 v245, 16, v55
	v_and_b32_e32 v55, 0xffff0000, v55
	v_readlane_b32 s0, v178, 63
	s_nop 1
	v_mov_b32_e32 v181, s0
	v_fmamk_f32 v181, v181, 0x3a800000, v161
	v_rsq_f32_e32 v179, v181
	s_nop 0
	v_mul_f32_e32 v246, v246, v179
	v_mul_f32_e32 v40, v40, v179
	v_mul_f32_e32 v247, v247, v179
	v_mul_f32_e32 v41, v41, v179
	v_mul_f32_e32 v248, v248, v179
	v_mul_f32_e32 v42, v42, v179
	v_mul_f32_e32 v249, v249, v179
	v_mul_f32_e32 v43, v43, v179
	v_mul_f32_e32 v250, v250, v179
	v_mul_f32_e32 v44, v44, v179
	v_mul_f32_e32 v251, v251, v179
	v_mul_f32_e32 v45, v45, v179
	v_mul_f32_e32 v176, v176, v179
	v_mul_f32_e32 v46, v46, v179
	v_mul_f32_e32 v177, v177, v179
	v_mul_f32_e32 v47, v47, v179
	v_mul_f32_e32 v246, v246, v56
	v_mul_f32_e32 v40, v40, v57
	v_mul_f32_e32 v247, v247, v58
	v_mul_f32_e32 v41, v41, v59
	v_mul_f32_e32 v248, v248, v60
	v_mul_f32_e32 v42, v42, v61
	v_mul_f32_e32 v249, v249, v62
	v_mul_f32_e32 v43, v43, v63
	v_mul_f32_e32 v250, v250, v64
	v_mul_f32_e32 v44, v44, v65
	v_mul_f32_e32 v251, v251, v66
	v_mul_f32_e32 v45, v45, v67
	v_mul_f32_e32 v176, v176, v68
	v_mul_f32_e32 v46, v46, v69
	v_mul_f32_e32 v177, v177, v70
	v_mul_f32_e32 v47, v47, v71
	v_fmac_f32_e32 v238, v88, v246
	v_fmac_f32_e32 v48, v89, v40
	v_fmac_f32_e32 v239, v90, v247
	v_fmac_f32_e32 v49, v91, v41
	v_fmac_f32_e32 v240, v92, v248
	v_fmac_f32_e32 v50, v93, v42
	v_fmac_f32_e32 v241, v94, v249
	v_fmac_f32_e32 v51, v95, v43
	v_fmac_f32_e32 v242, v96, v250
	v_fmac_f32_e32 v52, v97, v44
	v_fmac_f32_e32 v243, v98, v251
	v_fmac_f32_e32 v53, v99, v45
	v_fmac_f32_e32 v244, v100, v176
	v_fmac_f32_e32 v54, v101, v46
	v_fmac_f32_e32 v245, v102, v177
	v_fmac_f32_e32 v55, v103, v47
	v_cvt_pk_bf16_f32 v120, v238, v48
	v_cvt_pk_bf16_f32 v121, v239, v49
	global_store_dwordx2 v2, v[120:121], s[4:5] offset:0 nt
	v_cvt_pk_bf16_f32 v122, v240, v50
	v_cvt_pk_bf16_f32 v123, v241, v51
	global_store_dwordx2 v2, v[122:123], s[4:5] offset:512 nt
	v_cvt_pk_bf16_f32 v124, v242, v52
	v_cvt_pk_bf16_f32 v125, v243, v53
	global_store_dwordx2 v2, v[124:125], s[4:5] offset:1024 nt
	v_cvt_pk_bf16_f32 v126, v244, v54
	v_cvt_pk_bf16_f32 v127, v245, v55
	global_store_dwordx2 v2, v[126:127], s[4:5] offset:1536 nt
	v_mul_f32_e32 v178, v238, v238
	v_fmac_f32_e32 v178, v48, v48
	v_fmac_f32_e32 v178, v239, v239
	v_fmac_f32_e32 v178, v49, v49
	v_fmac_f32_e32 v178, v240, v240
	v_fmac_f32_e32 v178, v50, v50
	v_fmac_f32_e32 v178, v241, v241
	v_fmac_f32_e32 v178, v51, v51
	v_fmac_f32_e32 v178, v242, v242
	v_fmac_f32_e32 v178, v52, v52
	v_fmac_f32_e32 v178, v243, v243
	v_fmac_f32_e32 v178, v53, v53
	v_fmac_f32_e32 v178, v244, v244
	v_fmac_f32_e32 v178, v54, v54
	v_fmac_f32_e32 v178, v245, v245
	v_fmac_f32_e32 v178, v55, v55
	s_nop 1
	v_add_f32_dpp v178, v178, v178 quad_perm:[1,0,3,2] row_mask:0xf bank_mask:0xf bound_ctrl:1
	s_nop 1
	v_add_f32_dpp v178, v178, v178 quad_perm:[2,3,0,1] row_mask:0xf bank_mask:0xf bound_ctrl:1
	s_nop 1
	v_add_f32_dpp v178, v178, v178 row_half_mirror row_mask:0xf bank_mask:0xf bound_ctrl:1
	s_nop 1
	v_add_f32_dpp v178, v178, v178 row_mirror row_mask:0xf bank_mask:0xf bound_ctrl:1
	s_nop 1
	v_add_f32_dpp v178, v178, v178 row_bcast:15 row_mask:0xa bank_mask:0xf
	s_nop 1
	v_add_f32_dpp v178, v178, v178 row_bcast:31 row_mask:0xc bank_mask:0xf
	s_nop 0
	v_readlane_b32 s0, v178, 63
	s_nop 1
	v_mov_b32_e32 v181, s0
	v_fmamk_f32 v181, v181, 0x3a800000, v161
	v_rsq_f32_e32 v180, v181
	s_nop 0
	v_mul_f32_e32 v238, v238, v180
	v_mul_f32_e32 v48, v48, v180
	v_mul_f32_e32 v239, v239, v180
	v_mul_f32_e32 v49, v49, v180
	v_mul_f32_e32 v240, v240, v180
	v_mul_f32_e32 v50, v50, v180
	v_mul_f32_e32 v241, v241, v180
	v_mul_f32_e32 v51, v51, v180
	v_mul_f32_e32 v242, v242, v180
	v_mul_f32_e32 v52, v52, v180
	v_mul_f32_e32 v243, v243, v180
	v_mul_f32_e32 v53, v53, v180
	v_mul_f32_e32 v244, v244, v180
	v_mul_f32_e32 v54, v54, v180
	v_mul_f32_e32 v245, v245, v180
	v_mul_f32_e32 v55, v55, v180
	v_mul_f32_e32 v238, v238, v72
	v_mul_f32_e32 v48, v48, v73
	v_mul_f32_e32 v239, v239, v74
	v_mul_f32_e32 v49, v49, v75
	v_mul_f32_e32 v240, v240, v76
	v_mul_f32_e32 v50, v50, v77
	v_mul_f32_e32 v241, v241, v78
	v_mul_f32_e32 v51, v51, v79
	v_mul_f32_e32 v242, v242, v80
	v_mul_f32_e32 v52, v52, v81
	v_mul_f32_e32 v243, v243, v82
	v_mul_f32_e32 v53, v53, v83
	v_mul_f32_e32 v244, v244, v84
	v_mul_f32_e32 v54, v54, v85
	v_mul_f32_e32 v245, v245, v86
	v_mul_f32_e32 v55, v55, v87
	v_fma_f32 v238, v238, v104, v134
	v_fma_f32 v48, v48, v105, v135
	v_fma_f32 v239, v239, v106, v136
	v_fma_f32 v49, v49, v107, v137
	v_fma_f32 v240, v240, v108, v138
	v_fma_f32 v50, v50, v109, v139
	v_fma_f32 v241, v241, v110, v140
	v_fma_f32 v51, v51, v111, v141
	v_fma_f32 v242, v242, v112, v142
	v_fma_f32 v52, v52, v113, v143
	v_fma_f32 v243, v243, v114, v144
	v_fma_f32 v53, v53, v115, v145
	v_fma_f32 v244, v244, v116, v146
	v_fma_f32 v54, v54, v117, v147
	v_fma_f32 v245, v245, v118, v148
	v_fma_f32 v55, v55, v119, v149
	v_cvt_pk_bf16_f32 v150, v238, v48
	v_cvt_pk_bf16_f32 v151, v239, v49
	global_store_dwordx2 v2, v[150:151], s[8:9] offset:0
	v_cvt_pk_bf16_f32 v152, v240, v50
	v_cvt_pk_bf16_f32 v153, v241, v51
	global_store_dwordx2 v2, v[152:153], s[8:9] offset:512
	v_cvt_pk_bf16_f32 v154, v242, v52
	v_cvt_pk_bf16_f32 v155, v243, v53
	global_store_dwordx2 v2, v[154:155], s[8:9] offset:1024
	v_cvt_pk_bf16_f32 v156, v244, v54
	v_cvt_pk_bf16_f32 v157, v245, v55
	global_store_dwordx2 v2, v[156:157], s[8:9] offset:1536
	s_waitcnt vmcnt(28)
	v_lshlrev_b32_e32 v246, 16, v8
	v_and_b32_e32 v8, 0xffff0000, v8
	v_lshlrev_b32_e32 v247, 16, v9
	v_and_b32_e32 v9, 0xffff0000, v9
	v_lshlrev_b32_e32 v248, 16, v10
	v_and_b32_e32 v10, 0xffff0000, v10
	v_lshlrev_b32_e32 v249, 16, v11
	v_and_b32_e32 v11, 0xffff0000, v11
	v_lshlrev_b32_e32 v250, 16, v12
	v_and_b32_e32 v12, 0xffff0000, v12
	v_lshlrev_b32_e32 v251, 16, v13
	v_and_b32_e32 v13, 0xffff0000, v13
	v_lshlrev_b32_e32 v176, 16, v14
	v_and_b32_e32 v14, 0xffff0000, v14
	v_lshlrev_b32_e32 v177, 16, v15
	v_and_b32_e32 v15, 0xffff0000, v15
	v_mul_f32_e32 v178, v246, v246
	v_fmac_f32_e32 v178, v8, v8
	v_fmac_f32_e32 v178, v247, v247
	v_fmac_f32_e32 v178, v9, v9
	v_fmac_f32_e32 v178, v248, v248
	v_fmac_f32_e32 v178, v10, v10
	v_fmac_f32_e32 v178, v249, v249
	v_fmac_f32_e32 v178, v11, v11
	v_fmac_f32_e32 v178, v250, v250
	v_fmac_f32_e32 v178, v12, v12
	v_fmac_f32_e32 v178, v251, v251
	v_fmac_f32_e32 v178, v13, v13
	v_fmac_f32_e32 v178, v176, v176
	v_fmac_f32_e32 v178, v14, v14
	v_fmac_f32_e32 v178, v177, v177
	v_fmac_f32_e32 v178, v15, v15
	s_waitcnt vmcnt(24)
	v_lshlrev_b32_e32 v238, 16, v16
	v_and_b32_e32 v16, 0xffff0000, v16
	v_add_f32_dpp v178, v178, v178 quad_perm:[1,0,3,2] row_mask:0xf bank_mask:0xf bound_ctrl:1
	v_lshlrev_b32_e32 v239, 16, v17
	v_and_b32_e32 v17, 0xffff0000, v17
	v_add_f32_dpp v178, v178, v178 quad_perm:[2,3,0,1] row_mask:0xf bank_mask:0xf bound_ctrl:1
	v_lshlrev_b32_e32 v240, 16, v18
	v_and_b32_e32 v18, 0xffff0000, v18
	v_add_f32_dpp v178, v178, v178 row_half_mirror row_mask:0xf bank_mask:0xf bound_ctrl:1
	v_lshlrev_b32_e32 v241, 16, v19
	v_and_b32_e32 v19, 0xffff0000, v19
	v_add_f32_dpp v178, v178, v178 row_mirror row_mask:0xf bank_mask:0xf bound_ctrl:1
	v_lshlrev_b32_e32 v242, 16, v20
	v_and_b32_e32 v20, 0xffff0000, v20
	v_add_f32_dpp v178, v178, v178 row_bcast:15 row_mask:0xa bank_mask:0xf
	v_lshlrev_b32_e32 v243, 16, v21
	v_and_b32_e32 v21, 0xffff0000, v21
	v_add_f32_dpp v178, v178, v178 row_bcast:31 row_mask:0xc bank_mask:0xf
	v_lshlrev_b32_e32 v244, 16, v22
	v_and_b32_e32 v22, 0xffff0000, v22
	v_lshlrev_b32_e32 v245, 16, v23
	v_and_b32_e32 v23, 0xffff0000, v23
	v_readlane_b32 s0, v178, 63
	s_nop 1
	v_mov_b32_e32 v181, s0
	v_fmamk_f32 v181, v181, 0x3a800000, v161
	v_rsq_f32_e32 v179, v181
	s_nop 0
	v_mul_f32_e32 v246, v246, v179
	v_mul_f32_e32 v8, v8, v179
	v_mul_f32_e32 v247, v247, v179
	v_mul_f32_e32 v9, v9, v179
	v_mul_f32_e32 v248, v248, v179
	v_mul_f32_e32 v10, v10, v179
	v_mul_f32_e32 v249, v249, v179
	v_mul_f32_e32 v11, v11, v179
	v_mul_f32_e32 v250, v250, v179
	v_mul_f32_e32 v12, v12, v179
	v_mul_f32_e32 v251, v251, v179
	v_mul_f32_e32 v13, v13, v179
	v_mul_f32_e32 v176, v176, v179
	v_mul_f32_e32 v14, v14, v179
	v_mul_f32_e32 v177, v177, v179
	v_mul_f32_e32 v15, v15, v179
	v_mul_f32_e32 v246, v246, v56
	v_mul_f32_e32 v8, v8, v57
	v_mul_f32_e32 v247, v247, v58
	v_mul_f32_e32 v9, v9, v59
	v_mul_f32_e32 v248, v248, v60
	v_mul_f32_e32 v10, v10, v61
	v_mul_f32_e32 v249, v249, v62
	v_mul_f32_e32 v11, v11, v63
	v_mul_f32_e32 v250, v250, v64
	v_mul_f32_e32 v12, v12, v65
	v_mul_f32_e32 v251, v251, v66
	v_mul_f32_e32 v13, v13, v67
	v_mul_f32_e32 v176, v176, v68
	v_mul_f32_e32 v14, v14, v69
	v_mul_f32_e32 v177, v177, v70
	v_mul_f32_e32 v15, v15, v71
	v_fmac_f32_e32 v238, v88, v246
	v_fmac_f32_e32 v16, v89, v8
	v_fmac_f32_e32 v239, v90, v247
	v_fmac_f32_e32 v17, v91, v9
	v_fmac_f32_e32 v240, v92, v248
	v_fmac_f32_e32 v18, v93, v10
	v_fmac_f32_e32 v241, v94, v249
	v_fmac_f32_e32 v19, v95, v11
	v_fmac_f32_e32 v242, v96, v250
	v_fmac_f32_e32 v20, v97, v12
	v_fmac_f32_e32 v243, v98, v251
	v_fmac_f32_e32 v21, v99, v13
	v_fmac_f32_e32 v244, v100, v176
	v_fmac_f32_e32 v22, v101, v14
	v_fmac_f32_e32 v245, v102, v177
	v_fmac_f32_e32 v23, v103, v15
	v_cvt_pk_bf16_f32 v120, v238, v16
	v_cvt_pk_bf16_f32 v121, v239, v17
	global_store_dwordx2 v3, v[120:121], s[4:5] offset:0 nt
	v_cvt_pk_bf16_f32 v122, v240, v18
	v_cvt_pk_bf16_f32 v123, v241, v19
	global_store_dwordx2 v3, v[122:123], s[4:5] offset:512 nt
	v_cvt_pk_bf16_f32 v124, v242, v20
	v_cvt_pk_bf16_f32 v125, v243, v21
	global_store_dwordx2 v3, v[124:125], s[4:5] offset:1024 nt
	v_cvt_pk_bf16_f32 v126, v244, v22
	v_cvt_pk_bf16_f32 v127, v245, v23
	global_store_dwordx2 v3, v[126:127], s[4:5] offset:1536 nt
	v_mul_f32_e32 v178, v238, v238
	v_fmac_f32_e32 v178, v16, v16
	v_fmac_f32_e32 v178, v239, v239
	v_fmac_f32_e32 v178, v17, v17
	v_fmac_f32_e32 v178, v240, v240
	v_fmac_f32_e32 v178, v18, v18
	v_fmac_f32_e32 v178, v241, v241
	v_fmac_f32_e32 v178, v19, v19
	v_fmac_f32_e32 v178, v242, v242
	v_fmac_f32_e32 v178, v20, v20
	v_fmac_f32_e32 v178, v243, v243
	v_fmac_f32_e32 v178, v21, v21
	v_fmac_f32_e32 v178, v244, v244
	v_fmac_f32_e32 v178, v22, v22
	v_fmac_f32_e32 v178, v245, v245
	v_fmac_f32_e32 v178, v23, v23
	s_nop 1
	v_add_f32_dpp v178, v178, v178 quad_perm:[1,0,3,2] row_mask:0xf bank_mask:0xf bound_ctrl:1
	s_nop 1
	v_add_f32_dpp v178, v178, v178 quad_perm:[2,3,0,1] row_mask:0xf bank_mask:0xf bound_ctrl:1
	s_nop 1
	v_add_f32_dpp v178, v178, v178 row_half_mirror row_mask:0xf bank_mask:0xf bound_ctrl:1
	s_nop 1
	v_add_f32_dpp v178, v178, v178 row_mirror row_mask:0xf bank_mask:0xf bound_ctrl:1
	s_nop 1
	v_add_f32_dpp v178, v178, v178 row_bcast:15 row_mask:0xa bank_mask:0xf
	s_nop 1
	v_add_f32_dpp v178, v178, v178 row_bcast:31 row_mask:0xc bank_mask:0xf
	s_nop 0
	v_readlane_b32 s0, v178, 63
	s_nop 1
	v_mov_b32_e32 v181, s0
	v_fmamk_f32 v181, v181, 0x3a800000, v161
	v_rsq_f32_e32 v180, v181
	s_nop 0
	v_mul_f32_e32 v238, v238, v180
	v_mul_f32_e32 v16, v16, v180
	v_mul_f32_e32 v239, v239, v180
	v_mul_f32_e32 v17, v17, v180
	v_mul_f32_e32 v240, v240, v180
	v_mul_f32_e32 v18, v18, v180
	v_mul_f32_e32 v241, v241, v180
	v_mul_f32_e32 v19, v19, v180
	v_mul_f32_e32 v242, v242, v180
	v_mul_f32_e32 v20, v20, v180
	v_mul_f32_e32 v243, v243, v180
	v_mul_f32_e32 v21, v21, v180
	v_mul_f32_e32 v244, v244, v180
	v_mul_f32_e32 v22, v22, v180
	v_mul_f32_e32 v245, v245, v180
	v_mul_f32_e32 v23, v23, v180
	v_mul_f32_e32 v238, v238, v72
	v_mul_f32_e32 v16, v16, v73
	v_mul_f32_e32 v239, v239, v74
	v_mul_f32_e32 v17, v17, v75
	v_mul_f32_e32 v240, v240, v76
	v_mul_f32_e32 v18, v18, v77
	v_mul_f32_e32 v241, v241, v78
	v_mul_f32_e32 v19, v19, v79
	v_mul_f32_e32 v242, v242, v80
	v_mul_f32_e32 v20, v20, v81
	v_mul_f32_e32 v243, v243, v82
	v_mul_f32_e32 v21, v21, v83
	v_mul_f32_e32 v244, v244, v84
	v_mul_f32_e32 v22, v22, v85
	v_mul_f32_e32 v245, v245, v86
	v_mul_f32_e32 v23, v23, v87
	v_fma_f32 v238, v238, v104, v134
	v_fma_f32 v16, v16, v105, v135
	v_fma_f32 v239, v239, v106, v136
	v_fma_f32 v17, v17, v107, v137
	v_fma_f32 v240, v240, v108, v138
	v_fma_f32 v18, v18, v109, v139
	v_fma_f32 v241, v241, v110, v140
	v_fma_f32 v19, v19, v111, v141
	v_fma_f32 v242, v242, v112, v142
	v_fma_f32 v20, v20, v113, v143
	v_fma_f32 v243, v243, v114, v144
	v_fma_f32 v21, v21, v115, v145
	v_fma_f32 v244, v244, v116, v146
	v_fma_f32 v22, v22, v117, v147
	v_fma_f32 v245, v245, v118, v148
	v_fma_f32 v23, v23, v119, v149
	v_cvt_pk_bf16_f32 v150, v238, v16
	v_cvt_pk_bf16_f32 v151, v239, v17
	global_store_dwordx2 v3, v[150:151], s[8:9] offset:0
	v_cvt_pk_bf16_f32 v152, v240, v18
	v_cvt_pk_bf16_f32 v153, v241, v19
	global_store_dwordx2 v3, v[152:153], s[8:9] offset:512
	v_cvt_pk_bf16_f32 v154, v242, v20
	v_cvt_pk_bf16_f32 v155, v243, v21
	global_store_dwordx2 v3, v[154:155], s[8:9] offset:1024
	v_cvt_pk_bf16_f32 v156, v244, v22
	v_cvt_pk_bf16_f32 v157, v245, v23
	global_store_dwordx2 v3, v[156:157], s[8:9] offset:1536
	s_waitcnt vmcnt(28)
	v_lshlrev_b32_e32 v246, 16, v190
	v_and_b32_e32 v190, 0xffff0000, v190
	v_lshlrev_b32_e32 v247, 16, v191
	v_and_b32_e32 v191, 0xffff0000, v191
	v_lshlrev_b32_e32 v248, 16, v192
	v_and_b32_e32 v192, 0xffff0000, v192
	v_lshlrev_b32_e32 v249, 16, v193
	v_and_b32_e32 v193, 0xffff0000, v193
	v_lshlrev_b32_e32 v250, 16, v194
	v_and_b32_e32 v194, 0xffff0000, v194
	v_lshlrev_b32_e32 v251, 16, v195
	v_and_b32_e32 v195, 0xffff0000, v195
	v_lshlrev_b32_e32 v176, 16, v196
	v_and_b32_e32 v196, 0xffff0000, v196
	v_lshlrev_b32_e32 v177, 16, v197
	v_and_b32_e32 v197, 0xffff0000, v197
	v_mul_f32_e32 v178, v246, v246
	v_fmac_f32_e32 v178, v190, v190
	v_fmac_f32_e32 v178, v247, v247
	v_fmac_f32_e32 v178, v191, v191
	v_fmac_f32_e32 v178, v248, v248
	v_fmac_f32_e32 v178, v192, v192
	v_fmac_f32_e32 v178, v249, v249
	v_fmac_f32_e32 v178, v193, v193
	v_fmac_f32_e32 v178, v250, v250
	v_fmac_f32_e32 v178, v194, v194
	v_fmac_f32_e32 v178, v251, v251
	v_fmac_f32_e32 v178, v195, v195
	v_fmac_f32_e32 v178, v176, v176
	v_fmac_f32_e32 v178, v196, v196
	v_fmac_f32_e32 v178, v177, v177
	v_fmac_f32_e32 v178, v197, v197
	s_waitcnt vmcnt(24)
	v_lshlrev_b32_e32 v238, 16, v198
	v_and_b32_e32 v198, 0xffff0000, v198
	v_add_f32_dpp v178, v178, v178 quad_perm:[1,0,3,2] row_mask:0xf bank_mask:0xf bound_ctrl:1
	v_lshlrev_b32_e32 v239, 16, v199
	v_and_b32_e32 v199, 0xffff0000, v199
	v_add_f32_dpp v178, v178, v178 quad_perm:[2,3,0,1] row_mask:0xf bank_mask:0xf bound_ctrl:1
	v_lshlrev_b32_e32 v240, 16, v200
	v_and_b32_e32 v200, 0xffff0000, v200
	v_add_f32_dpp v178, v178, v178 row_half_mirror row_mask:0xf bank_mask:0xf bound_ctrl:1
	v_lshlrev_b32_e32 v241, 16, v201
	v_and_b32_e32 v201, 0xffff0000, v201
	v_add_f32_dpp v178, v178, v178 row_mirror row_mask:0xf bank_mask:0xf bound_ctrl:1
	v_lshlrev_b32_e32 v242, 16, v202
	v_and_b32_e32 v202, 0xffff0000, v202
	v_add_f32_dpp v178, v178, v178 row_bcast:15 row_mask:0xa bank_mask:0xf
	v_lshlrev_b32_e32 v243, 16, v203
	v_and_b32_e32 v203, 0xffff0000, v203
	v_add_f32_dpp v178, v178, v178 row_bcast:31 row_mask:0xc bank_mask:0xf
	v_lshlrev_b32_e32 v244, 16, v204
	v_and_b32_e32 v204, 0xffff0000, v204
	v_lshlrev_b32_e32 v245, 16, v205
	v_and_b32_e32 v205, 0xffff0000, v205
	v_readlane_b32 s0, v178, 63
	s_nop 1
	v_mov_b32_e32 v181, s0
	v_fmamk_f32 v181, v181, 0x3a800000, v161
	v_rsq_f32_e32 v179, v181
	s_nop 0
	v_mul_f32_e32 v246, v246, v179
	v_mul_f32_e32 v190, v190, v179
	v_mul_f32_e32 v247, v247, v179
	v_mul_f32_e32 v191, v191, v179
	v_mul_f32_e32 v248, v248, v179
	v_mul_f32_e32 v192, v192, v179
	v_mul_f32_e32 v249, v249, v179
	v_mul_f32_e32 v193, v193, v179
	v_mul_f32_e32 v250, v250, v179
	v_mul_f32_e32 v194, v194, v179
	v_mul_f32_e32 v251, v251, v179
	v_mul_f32_e32 v195, v195, v179
	v_mul_f32_e32 v176, v176, v179
	v_mul_f32_e32 v196, v196, v179
	v_mul_f32_e32 v177, v177, v179
	v_mul_f32_e32 v197, v197, v179
	v_mul_f32_e32 v246, v246, v56
	v_mul_f32_e32 v190, v190, v57
	v_mul_f32_e32 v247, v247, v58
	v_mul_f32_e32 v191, v191, v59
	v_mul_f32_e32 v248, v248, v60
	v_mul_f32_e32 v192, v192, v61
	v_mul_f32_e32 v249, v249, v62
	v_mul_f32_e32 v193, v193, v63
	v_mul_f32_e32 v250, v250, v64
	v_mul_f32_e32 v194, v194, v65
	v_mul_f32_e32 v251, v251, v66
	v_mul_f32_e32 v195, v195, v67
	v_mul_f32_e32 v176, v176, v68
	v_mul_f32_e32 v196, v196, v69
	v_mul_f32_e32 v177, v177, v70
	v_mul_f32_e32 v197, v197, v71
	v_fmac_f32_e32 v238, v88, v246
	v_fmac_f32_e32 v198, v89, v190
	v_fmac_f32_e32 v239, v90, v247
	v_fmac_f32_e32 v199, v91, v191
	v_fmac_f32_e32 v240, v92, v248
	v_fmac_f32_e32 v200, v93, v192
	v_fmac_f32_e32 v241, v94, v249
	v_fmac_f32_e32 v201, v95, v193
	v_fmac_f32_e32 v242, v96, v250
	v_fmac_f32_e32 v202, v97, v194
	v_fmac_f32_e32 v243, v98, v251
	v_fmac_f32_e32 v203, v99, v195
	v_fmac_f32_e32 v244, v100, v176
	v_fmac_f32_e32 v204, v101, v196
	v_fmac_f32_e32 v245, v102, v177
	v_fmac_f32_e32 v205, v103, v197
	v_cvt_pk_bf16_f32 v120, v238, v198
	v_cvt_pk_bf16_f32 v121, v239, v199
	global_store_dwordx2 v4, v[120:121], s[4:5] offset:0 nt
	v_cvt_pk_bf16_f32 v122, v240, v200
	v_cvt_pk_bf16_f32 v123, v241, v201
	global_store_dwordx2 v4, v[122:123], s[4:5] offset:512 nt
	v_cvt_pk_bf16_f32 v124, v242, v202
	v_cvt_pk_bf16_f32 v125, v243, v203
	global_store_dwordx2 v4, v[124:125], s[4:5] offset:1024 nt
	v_cvt_pk_bf16_f32 v126, v244, v204
	v_cvt_pk_bf16_f32 v127, v245, v205
	global_store_dwordx2 v4, v[126:127], s[4:5] offset:1536 nt
	v_mul_f32_e32 v178, v238, v238
	v_fmac_f32_e32 v178, v198, v198
	v_fmac_f32_e32 v178, v239, v239
	v_fmac_f32_e32 v178, v199, v199
	v_fmac_f32_e32 v178, v240, v240
	v_fmac_f32_e32 v178, v200, v200
	v_fmac_f32_e32 v178, v241, v241
	v_fmac_f32_e32 v178, v201, v201
	v_fmac_f32_e32 v178, v242, v242
	v_fmac_f32_e32 v178, v202, v202
	v_fmac_f32_e32 v178, v243, v243
	v_fmac_f32_e32 v178, v203, v203
	v_fmac_f32_e32 v178, v244, v244
	v_fmac_f32_e32 v178, v204, v204
	v_fmac_f32_e32 v178, v245, v245
	v_fmac_f32_e32 v178, v205, v205
	s_nop 1
	v_add_f32_dpp v178, v178, v178 quad_perm:[1,0,3,2] row_mask:0xf bank_mask:0xf bound_ctrl:1
	s_nop 1
	v_add_f32_dpp v178, v178, v178 quad_perm:[2,3,0,1] row_mask:0xf bank_mask:0xf bound_ctrl:1
	s_nop 1
	v_add_f32_dpp v178, v178, v178 row_half_mirror row_mask:0xf bank_mask:0xf bound_ctrl:1
	s_nop 1
	v_add_f32_dpp v178, v178, v178 row_mirror row_mask:0xf bank_mask:0xf bound_ctrl:1
	s_nop 1
	v_add_f32_dpp v178, v178, v178 row_bcast:15 row_mask:0xa bank_mask:0xf
	s_nop 1
	v_add_f32_dpp v178, v178, v178 row_bcast:31 row_mask:0xc bank_mask:0xf
	s_nop 0
	v_readlane_b32 s0, v178, 63
	s_nop 1
	v_mov_b32_e32 v181, s0
	v_fmamk_f32 v181, v181, 0x3a800000, v161
	v_rsq_f32_e32 v180, v181
	s_nop 0
	v_mul_f32_e32 v238, v238, v180
	v_mul_f32_e32 v198, v198, v180
	v_mul_f32_e32 v239, v239, v180
	v_mul_f32_e32 v199, v199, v180
	v_mul_f32_e32 v240, v240, v180
	v_mul_f32_e32 v200, v200, v180
	v_mul_f32_e32 v241, v241, v180
	v_mul_f32_e32 v201, v201, v180
	v_mul_f32_e32 v242, v242, v180
	v_mul_f32_e32 v202, v202, v180
	v_mul_f32_e32 v243, v243, v180
	v_mul_f32_e32 v203, v203, v180
	v_mul_f32_e32 v244, v244, v180
	v_mul_f32_e32 v204, v204, v180
	v_mul_f32_e32 v245, v245, v180
	v_mul_f32_e32 v205, v205, v180
	v_mul_f32_e32 v238, v238, v72
	v_mul_f32_e32 v198, v198, v73
	v_mul_f32_e32 v239, v239, v74
	v_mul_f32_e32 v199, v199, v75
	v_mul_f32_e32 v240, v240, v76
	v_mul_f32_e32 v200, v200, v77
	v_mul_f32_e32 v241, v241, v78
	v_mul_f32_e32 v201, v201, v79
	v_mul_f32_e32 v242, v242, v80
	v_mul_f32_e32 v202, v202, v81
	v_mul_f32_e32 v243, v243, v82
	v_mul_f32_e32 v203, v203, v83
	v_mul_f32_e32 v244, v244, v84
	v_mul_f32_e32 v204, v204, v85
	v_mul_f32_e32 v245, v245, v86
	v_mul_f32_e32 v205, v205, v87
	v_fma_f32 v238, v238, v104, v134
	v_fma_f32 v198, v198, v105, v135
	v_fma_f32 v239, v239, v106, v136
	v_fma_f32 v199, v199, v107, v137
	v_fma_f32 v240, v240, v108, v138
	v_fma_f32 v200, v200, v109, v139
	v_fma_f32 v241, v241, v110, v140
	v_fma_f32 v201, v201, v111, v141
	v_fma_f32 v242, v242, v112, v142
	v_fma_f32 v202, v202, v113, v143
	v_fma_f32 v243, v243, v114, v144
	v_fma_f32 v203, v203, v115, v145
	v_fma_f32 v244, v244, v116, v146
	v_fma_f32 v204, v204, v117, v147
	v_fma_f32 v245, v245, v118, v148
	v_fma_f32 v205, v205, v119, v149
	v_cvt_pk_bf16_f32 v150, v238, v198
	v_cvt_pk_bf16_f32 v151, v239, v199
	global_store_dwordx2 v4, v[150:151], s[8:9] offset:0
	v_cvt_pk_bf16_f32 v152, v240, v200
	v_cvt_pk_bf16_f32 v153, v241, v201
	global_store_dwordx2 v4, v[152:153], s[8:9] offset:512
	v_cvt_pk_bf16_f32 v154, v242, v202
	v_cvt_pk_bf16_f32 v155, v243, v203
	global_store_dwordx2 v4, v[154:155], s[8:9] offset:1024
	v_cvt_pk_bf16_f32 v156, v244, v204
	v_cvt_pk_bf16_f32 v157, v245, v205
	global_store_dwordx2 v4, v[156:157], s[8:9] offset:1536
	s_branch .LBB0_100
.Lrow2_last:
	v_readfirstlane_b32 s0, v160
	v_readlane_b32 s1, v252, 7
	s_lshr_b32 s0, s0, 6
	s_add_i32 s0, s0, s1
	v_readlane_b32 s62, v254, 34
	s_sub_u32 s64, s78, 0x110
	s_subb_u32 s65, s79, 0
	s_load_dwordx2 s[66:67], s[64:65], 0x40
	s_load_dwordx2 s[10:11], s[64:65], 0xf8
	s_lshl_b32 s63, s0, 11
	s_add_u32 s4, s84, 0x167ca000
	s_addc_u32 s5, s85, 0
	s_add_u32 s4, s4, s63
	s_addc_u32 s5, s5, 0
	s_add_u32 s6, s84, 0x112ca000
	s_addc_u32 s7, s85, 0
	s_add_u32 s6, s6, s63
	s_addc_u32 s7, s7, 0
	v_and_b32_e32 v0, 63, v160
	v_lshlrev_b32_e32 v1, 4, v0
	v_lshlrev_b32_e32 v0, 3, v0
	v_add_u32_e32 v2, 0x400000, v0
	v_add_u32_e32 v3, 0x800000, v0
	v_add_u32_e32 v4, 0xc00000, v0
	v_add_u32_e32 v5, 0x1000000, v0
	global_load_dwordx2 v[8:9], v5, s[6:7] offset:0 nt
	global_load_dwordx2 v[10:11], v5, s[6:7] offset:512 nt
	global_load_dwordx2 v[12:13], v5, s[6:7] offset:1024 nt
	global_load_dwordx2 v[14:15], v5, s[6:7] offset:1536 nt
	global_load_dwordx2 v[16:17], v5, s[4:5] offset:0 nt
	global_load_dwordx2 v[18:19], v5, s[4:5] offset:512 nt
	global_load_dwordx2 v[20:21], v5, s[4:5] offset:1024 nt
	global_load_dwordx2 v[22:23], v5, s[4:5] offset:1536 nt
	s_add_u32 s8, s84, 0xaeca000
	s_addc_u32 s9, s85, 0
	s_add_u32 s8, s8, s63
	s_addc_u32 s9, s9, 0
	s_lshr_b32 s69, s0, 10
	s_add_i32 s69, s69, 1
	s_mul_i32 s69, s69, 0x6000
	s_mul_i32 s68, s62, 0x12000
	s_mov_b32 s70, 0
	s_mul_i32 s71, s70, 0x12000
	s_lshl_b32 s70, s70, 14
	s_lshl_b32 s72, s62, 14
	s_add_i32 s72, s72, 0x3000
	s_add_u32 s16, s84, 0x6605000
	s_addc_u32 s17, s85, 0
	s_add_u32 s16, s16, s68
	s_addc_u32 s17, s17, 0
	s_add_u32 s20, s84, 0x6600000
	s_addc_u32 s21, s85, 0
	s_add_u32 s20, s20, s71
	s_addc_u32 s21, s21, 0
	s_add_u32 s18, s20, 0x1000
	s_addc_u32 s19, s21, 0
	s_add_u32 s22, s16, s69
	s_addc_u32 s23, s17, 0
	s_add_u32 s60, s20, s69
	s_addc_u32 s61, s21, 0
	s_add_u32 s26, s18, s69
	s_addc_u32 s27, s19, 0
	s_lshl_b32 s63, s63, 1
	s_waitcnt lgkmcnt(0)
	s_add_u32 s12, s66, s72
	s_addc_u32 s13, s67, 0
	s_add_u32 s14, s66, s70
	s_addc_u32 s15, s67, 0
	s_add_u32 s10, s10, s63
	s_addc_u32 s11, s11, 0
	global_load_dwordx4 v[190:193], v1, s[22:23] offset:0
	global_load_dwordx4 v[194:197], v1, s[22:23] offset:1024
	global_load_dwordx4 v[198:201], v1, s[22:23] offset:2048
	global_load_dwordx4 v[202:205], v1, s[22:23] offset:3072
	global_load_dwordx4 v[56:59], v1, s[12:13] offset:0
	global_load_dwordx4 v[60:63], v1, s[12:13] offset:1024
	global_load_dwordx4 v[64:67], v1, s[12:13] offset:2048
	global_load_dwordx4 v[68:71], v1, s[12:13] offset:3072
	global_load_dwordx2 v[24:25], v0, s[6:7] offset:0 nt
	global_load_dwordx2 v[26:27], v0, s[6:7] offset:512 nt
	global_load_dwordx2 v[28:29], v0, s[6:7] offset:1024 nt
	global_load_dwordx2 v[30:31], v0, s[6:7] offset:1536 nt
	global_load_dwordx2 v[32:33], v0, s[4:5] offset:0 nt
	global_load_dwordx2 v[34:35], v0, s[4:5] offset:512 nt
	global_load_dwordx2 v[36:37], v0, s[4:5] offset:1024 nt
	global_load_dwordx2 v[38:39], v0, s[4:5] offset:1536 nt
	global_load_dwordx4 v[88:91], v1, s[16:17] offset:0
	global_load_dwordx4 v[92:95], v1, s[16:17] offset:1024
	global_load_dwordx4 v[96:99], v1, s[16:17] offset:2048
	global_load_dwordx4 v[100:103], v1, s[16:17] offset:3072
	global_load_dwordx2 v[40:41], v2, s[6:7] offset:0 nt
	global_load_dwordx2 v[42:43], v2, s[6:7] offset:512 nt
	global_load_dwordx2 v[44:45], v2, s[6:7] offset:1024 nt
	global_load_dwordx2 v[46:47], v2, s[6:7] offset:1536 nt
	global_load_dwordx2 v[48:49], v2, s[4:5] offset:0 nt
	global_load_dwordx2 v[50:51], v2, s[4:5] offset:512 nt
	global_load_dwordx2 v[52:53], v2, s[4:5] offset:1024 nt
	global_load_dwordx2 v[54:55], v2, s[4:5] offset:1536 nt
	s_waitcnt vmcnt(32)
	v_lshlrev_b32_e32 v246, 16, v8
	v_and_b32_e32 v8, 0xffff0000, v8
	v_lshlrev_b32_e32 v247, 16, v9
	v_and_b32_e32 v9, 0xffff0000, v9
	v_lshlrev_b32_e32 v248, 16, v10
	v_and_b32_e32 v10, 0xffff0000, v10
	v_lshlrev_b32_e32 v249, 16, v11
	v_and_b32_e32 v11, 0xffff0000, v11
	v_lshlrev_b32_e32 v250, 16, v12
	v_and_b32_e32 v12, 0xffff0000, v12
	v_lshlrev_b32_e32 v251, 16, v13
	v_and_b32_e32 v13, 0xffff0000, v13
	v_lshlrev_b32_e32 v176, 16, v14
	v_and_b32_e32 v14, 0xffff0000, v14
	v_lshlrev_b32_e32 v177, 16, v15
	v_and_b32_e32 v15, 0xffff0000, v15
	v_mul_f32_e32 v178, v246, v246
	v_fmac_f32_e32 v178, v8, v8
	v_fmac_f32_e32 v178, v247, v247
	v_fmac_f32_e32 v178, v9, v9
	v_fmac_f32_e32 v178, v248, v248
	v_fmac_f32_e32 v178, v10, v10
	v_fmac_f32_e32 v178, v249, v249
	v_fmac_f32_e32 v178, v11, v11
	v_fmac_f32_e32 v178, v250, v250
	v_fmac_f32_e32 v178, v12, v12
	v_fmac_f32_e32 v178, v251, v251
	v_fmac_f32_e32 v178, v13, v13
	v_fmac_f32_e32 v178, v176, v176
	v_fmac_f32_e32 v178, v14, v14
	v_fmac_f32_e32 v178, v177, v177
	v_fmac_f32_e32 v178, v15, v15
	s_waitcnt vmcnt(28)
	v_lshlrev_b32_e32 v238, 16, v16
	v_and_b32_e32 v16, 0xffff0000, v16
	v_add_f32_dpp v178, v178, v178 quad_perm:[1,0,3,2] row_mask:0xf bank_mask:0xf bound_ctrl:1
	v_lshlrev_b32_e32 v239, 16, v17
	v_and_b32_e32 v17, 0xffff0000, v17
	v_add_f32_dpp v178, v178, v178 quad_perm:[2,3,0,1] row_mask:0xf bank_mask:0xf bound_ctrl:1
	v_lshlrev_b32_e32 v240, 16, v18
	v_and_b32_e32 v18, 0xffff0000, v18
	v_add_f32_dpp v178, v178, v178 row_half_mirror row_mask:0xf bank_mask:0xf bound_ctrl:1
	v_lshlrev_b32_e32 v241, 16, v19
	v_and_b32_e32 v19, 0xffff0000, v19
	v_add_f32_dpp v178, v178, v178 row_mirror row_mask:0xf bank_mask:0xf bound_ctrl:1
	v_lshlrev_b32_e32 v242, 16, v20
	v_and_b32_e32 v20, 0xffff0000, v20
	v_add_f32_dpp v178, v178, v178 row_bcast:15 row_mask:0xa bank_mask:0xf
	v_lshlrev_b32_e32 v243, 16, v21
	v_and_b32_e32 v21, 0xffff0000, v21
	v_add_f32_dpp v178, v178, v178 row_bcast:31 row_mask:0xc bank_mask:0xf
	v_lshlrev_b32_e32 v244, 16, v22
	v_and_b32_e32 v22, 0xffff0000, v22
	v_lshlrev_b32_e32 v245, 16, v23
	v_and_b32_e32 v23, 0xffff0000, v23
	v_readlane_b32 s0, v178, 63
	s_nop 1
	v_mov_b32_e32 v181, s0
	v_fmamk_f32 v181, v181, 0x3a800000, v161
	v_rsq_f32_e32 v179, v181
	s_nop 0
	s_waitcnt vmcnt(20)
	v_mul_f32_e32 v246, v246, v179
	v_mul_f32_e32 v8, v8, v179
	v_mul_f32_e32 v247, v247, v179
	v_mul_f32_e32 v9, v9, v179
	v_mul_f32_e32 v248, v248, v179
	v_mul_f32_e32 v10, v10, v179
	v_mul_f32_e32 v249, v249, v179
	v_mul_f32_e32 v11, v11, v179
	v_mul_f32_e32 v250, v250, v179
	v_mul_f32_e32 v12, v12, v179
	v_mul_f32_e32 v251, v251, v179
	v_mul_f32_e32 v13, v13, v179
	v_mul_f32_e32 v176, v176, v179
	v_mul_f32_e32 v14, v14, v179
	v_mul_f32_e32 v177, v177, v179
	v_mul_f32_e32 v15, v15, v179
	v_mul_f32_e32 v246, v246, v56
	v_mul_f32_e32 v8, v8, v57
	v_mul_f32_e32 v247, v247, v58
	v_mul_f32_e32 v9, v9, v59
	v_mul_f32_e32 v248, v248, v60
	v_mul_f32_e32 v10, v10, v61
	v_mul_f32_e32 v249, v249, v62
	v_mul_f32_e32 v11, v11, v63
	v_mul_f32_e32 v250, v250, v64
	v_mul_f32_e32 v12, v12, v65
	v_mul_f32_e32 v251, v251, v66
	v_mul_f32_e32 v13, v13, v67
	v_mul_f32_e32 v176, v176, v68
	v_mul_f32_e32 v14, v14, v69
	v_mul_f32_e32 v177, v177, v70
	v_mul_f32_e32 v15, v15, v71
	v_fmac_f32_e32 v238, v190, v246
	v_fmac_f32_e32 v16, v191, v8
	v_fmac_f32_e32 v239, v192, v247
	v_fmac_f32_e32 v17, v193, v9
	v_fmac_f32_e32 v240, v194, v248
	v_fmac_f32_e32 v18, v195, v10
	v_fmac_f32_e32 v241, v196, v249
	v_fmac_f32_e32 v19, v197, v11
	v_fmac_f32_e32 v242, v198, v250
	v_fmac_f32_e32 v20, v199, v12
	v_fmac_f32_e32 v243, v200, v251
	v_fmac_f32_e32 v21, v201, v13
	v_fmac_f32_e32 v244, v202, v176
	v_fmac_f32_e32 v22, v203, v14
	v_fmac_f32_e32 v245, v204, v177
	v_fmac_f32_e32 v23, v205, v15
	v_add_u32_e32 v181, 0x2000000, v1
	v_mov_b32_e32 v120, v238
	v_mov_b32_e32 v121, v16
	v_mov_b32_e32 v122, v239
	v_mov_b32_e32 v123, v17
	global_store_dwordx4 v181, v[120:123], s[10:11] offset:0
	v_mov_b32_e32 v124, v240
	v_mov_b32_e32 v125, v18
	v_mov_b32_e32 v126, v241
	v_mov_b32_e32 v127, v19
	global_store_dwordx4 v181, v[124:127], s[10:11] offset:1024
	v_mov_b32_e32 v150, v242
	v_mov_b32_e32 v151, v20
	v_mov_b32_e32 v152, v243
	v_mov_b32_e32 v153, v21
	global_store_dwordx4 v181, v[150:153], s[10:11] offset:2048
	v_mov_b32_e32 v154, v244
	v_mov_b32_e32 v155, v22
	v_mov_b32_e32 v156, v245
	v_mov_b32_e32 v157, v23
	global_store_dwordx4 v181, v[154:157], s[10:11] offset:3072
	global_load_dwordx2 v[8:9], v3, s[6:7] offset:0 nt
	global_load_dwordx2 v[10:11], v3, s[6:7] offset:512 nt
	global_load_dwordx2 v[12:13], v3, s[6:7] offset:1024 nt
	global_load_dwordx2 v[14:15], v3, s[6:7] offset:1536 nt
	global_load_dwordx2 v[16:17], v3, s[4:5] offset:0 nt
	global_load_dwordx2 v[18:19], v3, s[4:5] offset:512 nt
	global_load_dwordx2 v[20:21], v3, s[4:5] offset:1024 nt
	global_load_dwordx2 v[22:23], v3, s[4:5] offset:1536 nt
	global_load_dwordx2 v[190:191], v4, s[6:7] offset:0 nt
	global_load_dwordx2 v[192:193], v4, s[6:7] offset:512 nt
	global_load_dwordx2 v[194:195], v4, s[6:7] offset:1024 nt
	global_load_dwordx2 v[196:197], v4, s[6:7] offset:1536 nt
	global_load_dwordx2 v[198:199], v4, s[4:5] offset:0 nt
	global_load_dwordx2 v[200:201], v4, s[4:5] offset:512 nt
	global_load_dwordx2 v[202:203], v4, s[4:5] offset:1024 nt
	global_load_dwordx2 v[204:205], v4, s[4:5] offset:1536 nt
	s_waitcnt vmcnt(36)
	v_lshlrev_b32_e32 v246, 16, v24
	v_and_b32_e32 v24, 0xffff0000, v24
	v_lshlrev_b32_e32 v247, 16, v25
	v_and_b32_e32 v25, 0xffff0000, v25
	v_lshlrev_b32_e32 v248, 16, v26
	v_and_b32_e32 v26, 0xffff0000, v26
	v_lshlrev_b32_e32 v249, 16, v27
	v_and_b32_e32 v27, 0xffff0000, v27
	v_lshlrev_b32_e32 v250, 16, v28
	v_and_b32_e32 v28, 0xffff0000, v28
	v_lshlrev_b32_e32 v251, 16, v29
	v_and_b32_e32 v29, 0xffff0000, v29
	v_lshlrev_b32_e32 v176, 16, v30
	v_and_b32_e32 v30, 0xffff0000, v30
	v_lshlrev_b32_e32 v177, 16, v31
	v_and_b32_e32 v31, 0xffff0000, v31
	v_mul_f32_e32 v178, v246, v246
	v_fmac_f32_e32 v178, v24, v24
	v_fmac_f32_e32 v178, v247, v247
	v_fmac_f32_e32 v178, v25, v25
	v_fmac_f32_e32 v178, v248, v248
	v_fmac_f32_e32 v178, v26, v26
	v_fmac_f32_e32 v178, v249, v249
	v_fmac_f32_e32 v178, v27, v27
	v_fmac_f32_e32 v178, v250, v250
	v_fmac_f32_e32 v178, v28, v28
	v_fmac_f32_e32 v178, v251, v251
	v_fmac_f32_e32 v178, v29, v29
	v_fmac_f32_e32 v178, v176, v176
	v_fmac_f32_e32 v178, v30, v30
	v_fmac_f32_e32 v178, v177, v177
	v_fmac_f32_e32 v178, v31, v31
	s_waitcnt vmcnt(32)
	v_lshlrev_b32_e32 v238, 16, v32
	v_and_b32_e32 v32, 0xffff0000, v32
	v_add_f32_dpp v178, v178, v178 quad_perm:[1,0,3,2] row_mask:0xf bank_mask:0xf bound_ctrl:1
	v_lshlrev_b32_e32 v239, 16, v33
	v_and_b32_e32 v33, 0xffff0000, v33
	v_add_f32_dpp v178, v178, v178 quad_perm:[2,3,0,1] row_mask:0xf bank_mask:0xf bound_ctrl:1
	v_lshlrev_b32_e32 v240, 16, v34
	v_and_b32_e32 v34, 0xffff0000, v34
	v_add_f32_dpp v178, v178, v178 row_half_mirror row_mask:0xf bank_mask:0xf bound_ctrl:1
	v_lshlrev_b32_e32 v241, 16, v35
	v_and_b32_e32 v35, 0xffff0000, v35
	v_add_f32_dpp v178, v178, v178 row_mirror row_mask:0xf bank_mask:0xf bound_ctrl:1
	v_lshlrev_b32_e32 v242, 16, v36
	v_and_b32_e32 v36, 0xffff0000, v36
	v_add_f32_dpp v178, v178, v178 row_bcast:15 row_mask:0xa bank_mask:0xf
	v_lshlrev_b32_e32 v243, 16, v37
	v_and_b32_e32 v37, 0xffff0000, v37
	v_add_f32_dpp v178, v178, v178 row_bcast:31 row_mask:0xc bank_mask:0xf
	v_lshlrev_b32_e32 v244, 16, v38
	v_and_b32_e32 v38, 0xffff0000, v38
	v_lshlrev_b32_e32 v245, 16, v39
	v_and_b32_e32 v39, 0xffff0000, v39
	v_readlane_b32 s0, v178, 63
	s_nop 1
	v_mov_b32_e32 v181, s0
	v_fmamk_f32 v181, v181, 0x3a800000, v161
	v_rsq_f32_e32 v179, v181
	s_nop 0
	s_waitcnt vmcnt(28)
	v_mul_f32_e32 v246, v246, v179
	v_mul_f32_e32 v24, v24, v179
	v_mul_f32_e32 v247, v247, v179
	v_mul_f32_e32 v25, v25, v179
	v_mul_f32_e32 v248, v248, v179
	v_mul_f32_e32 v26, v26, v179
	v_mul_f32_e32 v249, v249, v179
	v_mul_f32_e32 v27, v27, v179
	v_mul_f32_e32 v250, v250, v179
	v_mul_f32_e32 v28, v28, v179
	v_mul_f32_e32 v251, v251, v179
	v_mul_f32_e32 v29, v29, v179
	v_mul_f32_e32 v176, v176, v179
	v_mul_f32_e32 v30, v30, v179
	v_mul_f32_e32 v177, v177, v179
	v_mul_f32_e32 v31, v31, v179
	v_mul_f32_e32 v246, v246, v56
	v_mul_f32_e32 v24, v24, v57
	v_mul_f32_e32 v247, v247, v58
	v_mul_f32_e32 v25, v25, v59
	v_mul_f32_e32 v248, v248, v60
	v_mul_f32_e32 v26, v26, v61
	v_mul_f32_e32 v249, v249, v62
	v_mul_f32_e32 v27, v27, v63
	v_mul_f32_e32 v250, v250, v64
	v_mul_f32_e32 v28, v28, v65
	v_mul_f32_e32 v251, v251, v66
	v_mul_f32_e32 v29, v29, v67
	v_mul_f32_e32 v176, v176, v68
	v_mul_f32_e32 v30, v30, v69
	v_mul_f32_e32 v177, v177, v70
	v_mul_f32_e32 v31, v31, v71
	v_fmac_f32_e32 v238, v88, v246
	v_fmac_f32_e32 v32, v89, v24
	v_fmac_f32_e32 v239, v90, v247
	v_fmac_f32_e32 v33, v91, v25
	v_fmac_f32_e32 v240, v92, v248
	v_fmac_f32_e32 v34, v93, v26
	v_fmac_f32_e32 v241, v94, v249
	v_fmac_f32_e32 v35, v95, v27
	v_fmac_f32_e32 v242, v96, v250
	v_fmac_f32_e32 v36, v97, v28
	v_fmac_f32_e32 v243, v98, v251
	v_fmac_f32_e32 v37, v99, v29
	v_fmac_f32_e32 v244, v100, v176
	v_fmac_f32_e32 v38, v101, v30
	v_fmac_f32_e32 v245, v102, v177
	v_fmac_f32_e32 v39, v103, v31
	v_add_u32_e32 v181, 0x0, v1
	v_mov_b32_e32 v120, v238
	v_mov_b32_e32 v121, v32
	v_mov_b32_e32 v122, v239
	v_mov_b32_e32 v123, v33
	global_store_dwordx4 v181, v[120:123], s[10:11] offset:0
	v_mov_b32_e32 v124, v240
	v_mov_b32_e32 v125, v34
	v_mov_b32_e32 v126, v241
	v_mov_b32_e32 v127, v35
	global_store_dwordx4 v181, v[124:127], s[10:11] offset:1024
	v_mov_b32_e32 v150, v242
	v_mov_b32_e32 v151, v36
	v_mov_b32_e32 v152, v243
	v_mov_b32_e32 v153, v37
	global_store_dwordx4 v181, v[150:153], s[10:11] offset:2048
	v_mov_b32_e32 v154, v244
	v_mov_b32_e32 v155, v38
	v_mov_b32_e32 v156, v245
	v_mov_b32_e32 v157, v39
	global_store_dwordx4 v181, v[154:157], s[10:11] offset:3072
	s_waitcnt vmcnt(28)
	v_lshlrev_b32_e32 v246, 16, v40
	v_and_b32_e32 v40, 0xffff0000, v40
	v_lshlrev_b32_e32 v247, 16, v41
	v_and_b32_e32 v41, 0xffff0000, v41
	v_lshlrev_b32_e32 v248, 16, v42
	v_and_b32_e32 v42, 0xffff0000, v42
	v_lshlrev_b32_e32 v249, 16, v43
	v_and_b32_e32 v43, 0xffff0000, v43
	v_lshlrev_b32_e32 v250, 16, v44
	v_and_b32_e32 v44, 0xffff0000, v44
	v_lshlrev_b32_e32 v251, 16, v45
	v_and_b32_e32 v45, 0xffff0000, v45
	v_lshlrev_b32_e32 v176, 16, v46
	v_and_b32_e32 v46, 0xffff0000, v46
	v_lshlrev_b32_e32 v177, 16, v47
	v_and_b32_e32 v47, 0xffff0000, v47
	v_mul_f32_e32 v178, v246, v246
	v_fmac_f32_e32 v178, v40, v40
	v_fmac_f32_e32 v178, v247, v247
	v_fmac_f32_e32 v178, v41, v41
	v_fmac_f32_e32 v178, v248, v248
	v_fmac_f32_e32 v178, v42, v42
	v_fmac_f32_e32 v178, v249, v249
	v_fmac_f32_e32 v178, v43, v43
	v_fmac_f32_e32 v178, v250, v250
	v_fmac_f32_e32 v178, v44, v44
	v_fmac_f32_e32 v178, v251, v251
	v_fmac_f32_e32 v178, v45, v45
	v_fmac_f32_e32 v178, v176, v176
	v_fmac_f32_e32 v178, v46, v46
	v_fmac_f32_e32 v178, v177, v177
	v_fmac_f32_e32 v178, v47, v47
	s_waitcnt vmcnt(24)
	v_lshlrev_b32_e32 v238, 16, v48
	v_and_b32_e32 v48, 0xffff0000, v48
	v_add_f32_dpp v178, v178, v178 quad_perm:[1,0,3,2] row_mask:0xf bank_mask:0xf bound_ctrl:1
	v_lshlrev_b32_e32 v239, 16, v49
	v_and_b32_e32 v49, 0xffff0000, v49
	v_add_f32_dpp v178, v178, v178 quad_perm:[2,3,0,1] row_mask:0xf bank_mask:0xf bound_ctrl:1
	v_lshlrev_b32_e32 v240, 16, v50
	v_and_b32_e32 v50, 0xffff0000, v50
	v_add_f32_dpp v178, v178, v178 row_half_mirror row_mask:0xf bank_mask:0xf bound_ctrl:1
	v_lshlrev_b32_e32 v241, 16, v51
	v_and_b32_e32 v51, 0xffff0000, v51
	v_add_f32_dpp v178, v178, v178 row_mirror row_mask:0xf bank_mask:0xf bound_ctrl:1
	v_lshlrev_b32_e32 v242, 16, v52
	v_and_b32_e32 v52, 0xffff0000, v52
	v_add_f32_dpp v178, v178, v178 row_bcast:15 row_mask:0xa bank_mask:0xf
	v_lshlrev_b32_e32 v243, 16, v53
	v_and_b32_e32 v53, 0xffff0000, v53
	v_add_f32_dpp v178, v178, v178 row_bcast:31 row_mask:0xc bank_mask:0xf
	v_lshlrev_b32_e32 v244, 16, v54
	v_and_b32_e32 v54, 0xffff0000, v54
	v_lshlrev_b32_e32 v245, 16, v55
	v_and_b32_e32 v55, 0xffff0000, v55
	v_readlane_b32 s0, v178, 63
	s_nop 1
	v_mov_b32_e32 v181, s0
	v_fmamk_f32 v181, v181, 0x3a800000, v161
	v_rsq_f32_e32 v179, v181
	s_nop 0
	v_mul_f32_e32 v246, v246, v179
	v_mul_f32_e32 v40, v40, v179
	v_mul_f32_e32 v247, v247, v179
	v_mul_f32_e32 v41, v41, v179
	v_mul_f32_e32 v248, v248, v179
	v_mul_f32_e32 v42, v42, v179
	v_mul_f32_e32 v249, v249, v179
	v_mul_f32_e32 v43, v43, v179
	v_mul_f32_e32 v250, v250, v179
	v_mul_f32_e32 v44, v44, v179
	v_mul_f32_e32 v251, v251, v179
	v_mul_f32_e32 v45, v45, v179
	v_mul_f32_e32 v176, v176, v179
	v_mul_f32_e32 v46, v46, v179
	v_mul_f32_e32 v177, v177, v179
	v_mul_f32_e32 v47, v47, v179
	v_mul_f32_e32 v246, v246, v56
	v_mul_f32_e32 v40, v40, v57
	v_mul_f32_e32 v247, v247, v58
	v_mul_f32_e32 v41, v41, v59
	v_mul_f32_e32 v248, v248, v60
	v_mul_f32_e32 v42, v42, v61
	v_mul_f32_e32 v249, v249, v62
	v_mul_f32_e32 v43, v43, v63
	v_mul_f32_e32 v250, v250, v64
	v_mul_f32_e32 v44, v44, v65
	v_mul_f32_e32 v251, v251, v66
	v_mul_f32_e32 v45, v45, v67
	v_mul_f32_e32 v176, v176, v68
	v_mul_f32_e32 v46, v46, v69
	v_mul_f32_e32 v177, v177, v70
	v_mul_f32_e32 v47, v47, v71
	v_fmac_f32_e32 v238, v88, v246
	v_fmac_f32_e32 v48, v89, v40
	v_fmac_f32_e32 v239, v90, v247
	v_fmac_f32_e32 v49, v91, v41
	v_fmac_f32_e32 v240, v92, v248
	v_fmac_f32_e32 v50, v93, v42
	v_fmac_f32_e32 v241, v94, v249
	v_fmac_f32_e32 v51, v95, v43
	v_fmac_f32_e32 v242, v96, v250
	v_fmac_f32_e32 v52, v97, v44
	v_fmac_f32_e32 v243, v98, v251
	v_fmac_f32_e32 v53, v99, v45
	v_fmac_f32_e32 v244, v100, v176
	v_fmac_f32_e32 v54, v101, v46
	v_fmac_f32_e32 v245, v102, v177
	v_fmac_f32_e32 v55, v103, v47
	v_add_u32_e32 v181, 0x800000, v1
	v_mov_b32_e32 v120, v238
	v_mov_b32_e32 v121, v48
	v_mov_b32_e32 v122, v239
	v_mov_b32_e32 v123, v49
	global_store_dwordx4 v181, v[120:123], s[10:11] offset:0
	v_mov_b32_e32 v124, v240
	v_mov_b32_e32 v125, v50
	v_mov_b32_e32 v126, v241
	v_mov_b32_e32 v127, v51
	global_store_dwordx4 v181, v[124:127], s[10:11] offset:1024
	v_mov_b32_e32 v150, v242
	v_mov_b32_e32 v151, v52
	v_mov_b32_e32 v152, v243
	v_mov_b32_e32 v153, v53
	global_store_dwordx4 v181, v[150:153], s[10:11] offset:2048
	v_mov_b32_e32 v154, v244
	v_mov_b32_e32 v155, v54
	v_mov_b32_e32 v156, v245
	v_mov_b32_e32 v157, v55
	global_store_dwordx4 v181, v[154:157], s[10:11] offset:3072
	s_waitcnt vmcnt(20)
	v_lshlrev_b32_e32 v246, 16, v8
	v_and_b32_e32 v8, 0xffff0000, v8
	v_lshlrev_b32_e32 v247, 16, v9
	v_and_b32_e32 v9, 0xffff0000, v9
	v_lshlrev_b32_e32 v248, 16, v10
	v_and_b32_e32 v10, 0xffff0000, v10
	v_lshlrev_b32_e32 v249, 16, v11
	v_and_b32_e32 v11, 0xffff0000, v11
	v_lshlrev_b32_e32 v250, 16, v12
	v_and_b32_e32 v12, 0xffff0000, v12
	v_lshlrev_b32_e32 v251, 16, v13
	v_and_b32_e32 v13, 0xffff0000, v13
	v_lshlrev_b32_e32 v176, 16, v14
	v_and_b32_e32 v14, 0xffff0000, v14
	v_lshlrev_b32_e32 v177, 16, v15
	v_and_b32_e32 v15, 0xffff0000, v15
	v_mul_f32_e32 v178, v246, v246
	v_fmac_f32_e32 v178, v8, v8
	v_fmac_f32_e32 v178, v247, v247
	v_fmac_f32_e32 v178, v9, v9
	v_fmac_f32_e32 v178, v248, v248
	v_fmac_f32_e32 v178, v10, v10
	v_fmac_f32_e32 v178, v249, v249
	v_fmac_f32_e32 v178, v11, v11
	v_fmac_f32_e32 v178, v250, v250
	v_fmac_f32_e32 v178, v12, v12
	v_fmac_f32_e32 v178, v251, v251
	v_fmac_f32_e32 v178, v13, v13
	v_fmac_f32_e32 v178, v176, v176
	v_fmac_f32_e32 v178, v14, v14
	v_fmac_f32_e32 v178, v177, v177
	v_fmac_f32_e32 v178, v15, v15
	s_waitcnt vmcnt(16)
	v_lshlrev_b32_e32 v238, 16, v16
	v_and_b32_e32 v16, 0xffff0000, v16
	v_add_f32_dpp v178, v178, v178 quad_perm:[1,0,3,2] row_mask:0xf bank_mask:0xf bound_ctrl:1
	v_lshlrev_b32_e32 v239, 16, v17
	v_and_b32_e32 v17, 0xffff0000, v17
	v_add_f32_dpp v178, v178, v178 quad_perm:[2,3,0,1] row_mask:0xf bank_mask:0xf bound_ctrl:1
	v_lshlrev_b32_e32 v240, 16, v18
	v_and_b32_e32 v18, 0xffff0000, v18
	v_add_f32_dpp v178, v178, v178 row_half_mirror row_mask:0xf bank_mask:0xf bound_ctrl:1
	v_lshlrev_b32_e32 v241, 16, v19
	v_and_b32_e32 v19, 0xffff0000, v19
	v_add_f32_dpp v178, v178, v178 row_mirror row_mask:0xf bank_mask:0xf bound_ctrl:1
	v_lshlrev_b32_e32 v242, 16, v20
	v_and_b32_e32 v20, 0xffff0000, v20
	v_add_f32_dpp v178, v178, v178 row_bcast:15 row_mask:0xa bank_mask:0xf
	v_lshlrev_b32_e32 v243, 16, v21
	v_and_b32_e32 v21, 0xffff0000, v21
	v_add_f32_dpp v178, v178, v178 row_bcast:31 row_mask:0xc bank_mask:0xf
	v_lshlrev_b32_e32 v244, 16, v22
	v_and_b32_e32 v22, 0xffff0000, v22
	v_lshlrev_b32_e32 v245, 16, v23
	v_and_b32_e32 v23, 0xffff0000, v23
	v_readlane_b32 s0, v178, 63
	s_nop 1
	v_mov_b32_e32 v181, s0
	v_fmamk_f32 v181, v181, 0x3a800000, v161
	v_rsq_f32_e32 v179, v181
	s_nop 0
	v_mul_f32_e32 v246, v246, v179
	v_mul_f32_e32 v8, v8, v179
	v_mul_f32_e32 v247, v247, v179
	v_mul_f32_e32 v9, v9, v179
	v_mul_f32_e32 v248, v248, v179
	v_mul_f32_e32 v10, v10, v179
	v_mul_f32_e32 v249, v249, v179
	v_mul_f32_e32 v11, v11, v179
	v_mul_f32_e32 v250, v250, v179
	v_mul_f32_e32 v12, v12, v179
	v_mul_f32_e32 v251, v251, v179
	v_mul_f32_e32 v13, v13, v179
	v_mul_f32_e32 v176, v176, v179
	v_mul_f32_e32 v14, v14, v179
	v_mul_f32_e32 v177, v177, v179
	v_mul_f32_e32 v15, v15, v179
	v_mul_f32_e32 v246, v246, v56
	v_mul_f32_e32 v8, v8, v57
	v_mul_f32_e32 v247, v247, v58
	v_mul_f32_e32 v9, v9, v59
	v_mul_f32_e32 v248, v248, v60
	v_mul_f32_e32 v10, v10, v61
	v_mul_f32_e32 v249, v249, v62
	v_mul_f32_e32 v11, v11, v63
	v_mul_f32_e32 v250, v250, v64
	v_mul_f32_e32 v12, v12, v65
	v_mul_f32_e32 v251, v251, v66
	v_mul_f32_e32 v13, v13, v67
	v_mul_f32_e32 v176, v176, v68
	v_mul_f32_e32 v14, v14, v69
	v_mul_f32_e32 v177, v177, v70
	v_mul_f32_e32 v15, v15, v71
	v_fmac_f32_e32 v238, v88, v246
	v_fmac_f32_e32 v16, v89, v8
	v_fmac_f32_e32 v239, v90, v247
	v_fmac_f32_e32 v17, v91, v9
	v_fmac_f32_e32 v240, v92, v248
	v_fmac_f32_e32 v18, v93, v10
	v_fmac_f32_e32 v241, v94, v249
	v_fmac_f32_e32 v19, v95, v11
	v_fmac_f32_e32 v242, v96, v250
	v_fmac_f32_e32 v20, v97, v12
	v_fmac_f32_e32 v243, v98, v251
	v_fmac_f32_e32 v21, v99, v13
	v_fmac_f32_e32 v244, v100, v176
	v_fmac_f32_e32 v22, v101, v14
	v_fmac_f32_e32 v245, v102, v177
	v_fmac_f32_e32 v23, v103, v15
	v_add_u32_e32 v181, 0x1000000, v1
	v_mov_b32_e32 v120, v238
	v_mov_b32_e32 v121, v16
	v_mov_b32_e32 v122, v239
	v_mov_b32_e32 v123, v17
	global_store_dwordx4 v181, v[120:123], s[10:11] offset:0
	v_mov_b32_e32 v124, v240
	v_mov_b32_e32 v125, v18
	v_mov_b32_e32 v126, v241
	v_mov_b32_e32 v127, v19
	global_store_dwordx4 v181, v[124:127], s[10:11] offset:1024
	v_mov_b32_e32 v150, v242
	v_mov_b32_e32 v151, v20
	v_mov_b32_e32 v152, v243
	v_mov_b32_e32 v153, v21
	global_store_dwordx4 v181, v[150:153], s[10:11] offset:2048
	v_mov_b32_e32 v154, v244
	v_mov_b32_e32 v155, v22
	v_mov_b32_e32 v156, v245
	v_mov_b32_e32 v157, v23
	global_store_dwordx4 v181, v[154:157], s[10:11] offset:3072
	s_waitcnt vmcnt(16)
	v_lshlrev_b32_e32 v246, 16, v190
	v_and_b32_e32 v190, 0xffff0000, v190
	v_lshlrev_b32_e32 v247, 16, v191
	v_and_b32_e32 v191, 0xffff0000, v191
	v_lshlrev_b32_e32 v248, 16, v192
	v_and_b32_e32 v192, 0xffff0000, v192
	v_lshlrev_b32_e32 v249, 16, v193
	v_and_b32_e32 v193, 0xffff0000, v193
	v_lshlrev_b32_e32 v250, 16, v194
	v_and_b32_e32 v194, 0xffff0000, v194
	v_lshlrev_b32_e32 v251, 16, v195
	v_and_b32_e32 v195, 0xffff0000, v195
	v_lshlrev_b32_e32 v176, 16, v196
	v_and_b32_e32 v196, 0xffff0000, v196
	v_lshlrev_b32_e32 v177, 16, v197
	v_and_b32_e32 v197, 0xffff0000, v197
	v_mul_f32_e32 v178, v246, v246
	v_fmac_f32_e32 v178, v190, v190
	v_fmac_f32_e32 v178, v247, v247
	v_fmac_f32_e32 v178, v191, v191
	v_fmac_f32_e32 v178, v248, v248
	v_fmac_f32_e32 v178, v192, v192
	v_fmac_f32_e32 v178, v249, v249
	v_fmac_f32_e32 v178, v193, v193
	v_fmac_f32_e32 v178, v250, v250
	v_fmac_f32_e32 v178, v194, v194
	v_fmac_f32_e32 v178, v251, v251
	v_fmac_f32_e32 v178, v195, v195
	v_fmac_f32_e32 v178, v176, v176
	v_fmac_f32_e32 v178, v196, v196
	v_fmac_f32_e32 v178, v177, v177
	v_fmac_f32_e32 v178, v197, v197
	s_waitcnt vmcnt(12)
	v_lshlrev_b32_e32 v238, 16, v198
	v_and_b32_e32 v198, 0xffff0000, v198
	v_add_f32_dpp v178, v178, v178 quad_perm:[1,0,3,2] row_mask:0xf bank_mask:0xf bound_ctrl:1
	v_lshlrev_b32_e32 v239, 16, v199
	v_and_b32_e32 v199, 0xffff0000, v199
	v_add_f32_dpp v178, v178, v178 quad_perm:[2,3,0,1] row_mask:0xf bank_mask:0xf bound_ctrl:1
	v_lshlrev_b32_e32 v240, 16, v200
	v_and_b32_e32 v200, 0xffff0000, v200
	v_add_f32_dpp v178, v178, v178 row_half_mirror row_mask:0xf bank_mask:0xf bound_ctrl:1
	v_lshlrev_b32_e32 v241, 16, v201
	v_and_b32_e32 v201, 0xffff0000, v201
	v_add_f32_dpp v178, v178, v178 row_mirror row_mask:0xf bank_mask:0xf bound_ctrl:1
	v_lshlrev_b32_e32 v242, 16, v202
	v_and_b32_e32 v202, 0xffff0000, v202
	v_add_f32_dpp v178, v178, v178 row_bcast:15 row_mask:0xa bank_mask:0xf
	v_lshlrev_b32_e32 v243, 16, v203
	v_and_b32_e32 v203, 0xffff0000, v203
	v_add_f32_dpp v178, v178, v178 row_bcast:31 row_mask:0xc bank_mask:0xf
	v_lshlrev_b32_e32 v244, 16, v204
	v_and_b32_e32 v204, 0xffff0000, v204
	v_lshlrev_b32_e32 v245, 16, v205
	v_and_b32_e32 v205, 0xffff0000, v205
	v_readlane_b32 s0, v178, 63
	s_nop 1
	v_mov_b32_e32 v181, s0
	v_fmamk_f32 v181, v181, 0x3a800000, v161
	v_rsq_f32_e32 v179, v181
	s_nop 0
	v_mul_f32_e32 v246, v246, v179
	v_mul_f32_e32 v190, v190, v179
	v_mul_f32_e32 v247, v247, v179
	v_mul_f32_e32 v191, v191, v179
	v_mul_f32_e32 v248, v248, v179
	v_mul_f32_e32 v192, v192, v179
	v_mul_f32_e32 v249, v249, v179
	v_mul_f32_e32 v193, v193, v179
	v_mul_f32_e32 v250, v250, v179
	v_mul_f32_e32 v194, v194, v179
	v_mul_f32_e32 v251, v251, v179
	v_mul_f32_e32 v195, v195, v179
	v_mul_f32_e32 v176, v176, v179
	v_mul_f32_e32 v196, v196, v179
	v_mul_f32_e32 v177, v177, v179
	v_mul_f32_e32 v197, v197, v179
	v_mul_f32_e32 v246, v246, v56
	v_mul_f32_e32 v190, v190, v57
	v_mul_f32_e32 v247, v247, v58
	v_mul_f32_e32 v191, v191, v59
	v_mul_f32_e32 v248, v248, v60
	v_mul_f32_e32 v192, v192, v61
	v_mul_f32_e32 v249, v249, v62
	v_mul_f32_e32 v193, v193, v63
	v_mul_f32_e32 v250, v250, v64
	v_mul_f32_e32 v194, v194, v65
	v_mul_f32_e32 v251, v251, v66
	v_mul_f32_e32 v195, v195, v67
	v_mul_f32_e32 v176, v176, v68
	v_mul_f32_e32 v196, v196, v69
	v_mul_f32_e32 v177, v177, v70
	v_mul_f32_e32 v197, v197, v71
	v_fmac_f32_e32 v238, v88, v246
	v_fmac_f32_e32 v198, v89, v190
	v_fmac_f32_e32 v239, v90, v247
	v_fmac_f32_e32 v199, v91, v191
	v_fmac_f32_e32 v240, v92, v248
	v_fmac_f32_e32 v200, v93, v192
	v_fmac_f32_e32 v241, v94, v249
	v_fmac_f32_e32 v201, v95, v193
	v_fmac_f32_e32 v242, v96, v250
	v_fmac_f32_e32 v202, v97, v194
	v_fmac_f32_e32 v243, v98, v251
	v_fmac_f32_e32 v203, v99, v195
	v_fmac_f32_e32 v244, v100, v176
	v_fmac_f32_e32 v204, v101, v196
	v_fmac_f32_e32 v245, v102, v177
	v_fmac_f32_e32 v205, v103, v197
	v_add_u32_e32 v181, 0x1800000, v1
	v_mov_b32_e32 v120, v238
	v_mov_b32_e32 v121, v198
	v_mov_b32_e32 v122, v239
	v_mov_b32_e32 v123, v199
	global_store_dwordx4 v181, v[120:123], s[10:11] offset:0
	v_mov_b32_e32 v124, v240
	v_mov_b32_e32 v125, v200
	v_mov_b32_e32 v126, v241
	v_mov_b32_e32 v127, v201
	global_store_dwordx4 v181, v[124:127], s[10:11] offset:1024
	v_mov_b32_e32 v150, v242
	v_mov_b32_e32 v151, v202
	v_mov_b32_e32 v152, v243
	v_mov_b32_e32 v153, v203
	global_store_dwordx4 v181, v[150:153], s[10:11] offset:2048
	v_mov_b32_e32 v154, v244
	v_mov_b32_e32 v155, v204
	v_mov_b32_e32 v156, v245
	v_mov_b32_e32 v157, v205
	global_store_dwordx4 v181, v[154:157], s[10:11] offset:3072
	s_branch .LBB0_100

.LBB0_168:
	s_andn2_b64 vcc, exec, s[4:5]
	s_cbranch_vccnz .LBB0_213
	v_readlane_b32 s0, v254, 40
	s_cmp_gt_i32 s0, 4
	s_mov_b64 s[0:1], -1
	s_cbranch_scc0 .LBB0_190
	v_readfirstlane_b32 s0, v160
	v_readlane_b32 s1, v252, 7
	s_lshr_b32 s0, s0, 6
	s_add_i32 s0, s0, s1
	v_readlane_b32 s62, v254, 34
	s_sub_u32 s64, s78, 0x110
	s_subb_u32 s65, s79, 0
	s_load_dwordx2 s[66:67], s[64:65], 0x40
	s_load_dwordx2 s[10:11], s[64:65], 0xf8
	s_lshl_b32 s63, s0, 11
	s_add_u32 s4, s84, 0x167ca000
	s_addc_u32 s5, s85, 0
	s_add_u32 s4, s4, s63
	s_addc_u32 s5, s5, 0
	s_add_u32 s6, s84, 0x112ca000
	s_addc_u32 s7, s85, 0
	s_add_u32 s6, s6, s63
	s_addc_u32 s7, s7, 0
	v_and_b32_e32 v0, 63, v160
	v_lshlrev_b32_e32 v1, 4, v0
	v_lshlrev_b32_e32 v0, 3, v0
	v_add_u32_e32 v2, 0x400000, v0
	v_add_u32_e32 v3, 0x800000, v0
	v_add_u32_e32 v4, 0xc00000, v0
	v_add_u32_e32 v5, 0x1000000, v0
	global_load_dwordx2 v[8:9], v5, s[6:7] offset:0 nt
	global_load_dwordx2 v[10:11], v5, s[6:7] offset:512 nt
	global_load_dwordx2 v[12:13], v5, s[6:7] offset:1024 nt
	global_load_dwordx2 v[14:15], v5, s[6:7] offset:1536 nt
	global_load_dwordx2 v[16:17], v5, s[4:5] offset:0 nt
	global_load_dwordx2 v[18:19], v5, s[4:5] offset:512 nt
	global_load_dwordx2 v[20:21], v5, s[4:5] offset:1024 nt
	global_load_dwordx2 v[22:23], v5, s[4:5] offset:1536 nt
	s_add_u32 s8, s84, 0xaeca000
	s_addc_u32 s9, s85, 0
	s_add_u32 s8, s8, s63
	s_addc_u32 s9, s9, 0
	s_lshr_b32 s69, s0, 10
	s_add_i32 s69, s69, 1
	s_mul_i32 s69, s69, 0x6000
	s_mul_i32 s68, s62, 0x12000
	s_lshl_b32 s72, s62, 14
	s_add_i32 s70, s72, 0x2000
	s_add_i32 s72, s72, 0x1000
	s_add_u32 s16, s84, 0x6602000
	s_addc_u32 s17, s85, 0
	s_add_u32 s16, s16, s68
	s_addc_u32 s17, s17, 0
	s_add_u32 s20, s16, 0x1000
	s_addc_u32 s21, s17, 0
	s_add_u32 s18, s16, 0x2000
	s_addc_u32 s19, s17, 0
	s_add_u32 s22, s16, s69
	s_addc_u32 s23, s17, 0
	s_add_u32 s60, s20, s69
	s_addc_u32 s61, s21, 0
	s_add_u32 s26, s18, s69
	s_addc_u32 s27, s19, 0
	s_lshl_b32 s63, s63, 1
	s_waitcnt lgkmcnt(0)
	s_add_u32 s12, s66, s72
	s_addc_u32 s13, s67, 0
	s_add_u32 s14, s66, s70
	s_addc_u32 s15, s67, 0
	s_add_u32 s10, s10, s63
	s_addc_u32 s11, s11, 0
	global_load_dwordx4 v[190:193], v1, s[22:23] offset:0
	global_load_dwordx4 v[194:197], v1, s[22:23] offset:1024
	global_load_dwordx4 v[198:201], v1, s[22:23] offset:2048
	global_load_dwordx4 v[202:205], v1, s[22:23] offset:3072
	global_load_dwordx4 v[56:59], v1, s[12:13] offset:0
	global_load_dwordx4 v[60:63], v1, s[12:13] offset:1024
	global_load_dwordx4 v[64:67], v1, s[12:13] offset:2048
	global_load_dwordx4 v[68:71], v1, s[12:13] offset:3072
	global_load_dwordx4 v[72:75], v1, s[14:15] offset:0
	global_load_dwordx4 v[76:79], v1, s[14:15] offset:1024
	global_load_dwordx4 v[80:83], v1, s[14:15] offset:2048
	global_load_dwordx4 v[84:87], v1, s[14:15] offset:3072
	global_load_dwordx4 v[206:209], v1, s[26:27] offset:0
	global_load_dwordx4 v[210:213], v1, s[26:27] offset:1024
	global_load_dwordx4 v[214:217], v1, s[26:27] offset:2048
	global_load_dwordx4 v[218:221], v1, s[26:27] offset:3072
	global_load_dwordx4 v[222:225], v1, s[60:61] offset:0
	global_load_dwordx4 v[226:229], v1, s[60:61] offset:1024
	global_load_dwordx4 v[230:233], v1, s[60:61] offset:2048
	global_load_dwordx4 v[234:237], v1, s[60:61] offset:3072
	global_load_dwordx2 v[24:25], v0, s[6:7] offset:0 nt
	global_load_dwordx2 v[26:27], v0, s[6:7] offset:512 nt
	global_load_dwordx2 v[28:29], v0, s[6:7] offset:1024 nt
	global_load_dwordx2 v[30:31], v0, s[6:7] offset:1536 nt
	global_load_dwordx2 v[32:33], v0, s[4:5] offset:0 nt
	global_load_dwordx2 v[34:35], v0, s[4:5] offset:512 nt
	global_load_dwordx2 v[36:37], v0, s[4:5] offset:1024 nt
	global_load_dwordx2 v[38:39], v0, s[4:5] offset:1536 nt
	global_load_dwordx4 v[88:91], v1, s[16:17] offset:0
	global_load_dwordx4 v[92:95], v1, s[16:17] offset:1024
	global_load_dwordx4 v[96:99], v1, s[16:17] offset:2048
	global_load_dwordx4 v[100:103], v1, s[16:17] offset:3072
	global_load_dwordx4 v[104:107], v1, s[18:19] offset:0
	global_load_dwordx4 v[108:111], v1, s[18:19] offset:1024
	global_load_dwordx4 v[112:115], v1, s[18:19] offset:2048
	global_load_dwordx4 v[116:119], v1, s[18:19] offset:3072
	global_load_dwordx4 v[134:137], v1, s[20:21] offset:0
	global_load_dwordx4 v[138:141], v1, s[20:21] offset:1024
	global_load_dwordx4 v[142:145], v1, s[20:21] offset:2048
	global_load_dwordx4 v[146:149], v1, s[20:21] offset:3072
	global_load_dwordx2 v[40:41], v2, s[6:7] offset:0 nt
	global_load_dwordx2 v[42:43], v2, s[6:7] offset:512 nt
	global_load_dwordx2 v[44:45], v2, s[6:7] offset:1024 nt
	global_load_dwordx2 v[46:47], v2, s[6:7] offset:1536 nt
	global_load_dwordx2 v[48:49], v2, s[4:5] offset:0 nt
	global_load_dwordx2 v[50:51], v2, s[4:5] offset:512 nt
	global_load_dwordx2 v[52:53], v2, s[4:5] offset:1024 nt
	global_load_dwordx2 v[54:55], v2, s[4:5] offset:1536 nt
	s_waitcnt vmcnt(52)
	v_lshlrev_b32_e32 v246, 16, v8
	v_and_b32_e32 v8, 0xffff0000, v8
	v_lshlrev_b32_e32 v247, 16, v9
	v_and_b32_e32 v9, 0xffff0000, v9
	v_lshlrev_b32_e32 v248, 16, v10
	v_and_b32_e32 v10, 0xffff0000, v10
	v_lshlrev_b32_e32 v249, 16, v11
	v_and_b32_e32 v11, 0xffff0000, v11
	v_lshlrev_b32_e32 v250, 16, v12
	v_and_b32_e32 v12, 0xffff0000, v12
	v_lshlrev_b32_e32 v251, 16, v13
	v_and_b32_e32 v13, 0xffff0000, v13
	v_lshlrev_b32_e32 v176, 16, v14
	v_and_b32_e32 v14, 0xffff0000, v14
	v_lshlrev_b32_e32 v177, 16, v15
	v_and_b32_e32 v15, 0xffff0000, v15
	v_mul_f32_e32 v178, v246, v246
	v_fmac_f32_e32 v178, v8, v8
	v_fmac_f32_e32 v178, v247, v247
	v_fmac_f32_e32 v178, v9, v9
	v_fmac_f32_e32 v178, v248, v248
	v_fmac_f32_e32 v178, v10, v10
	v_fmac_f32_e32 v178, v249, v249
	v_fmac_f32_e32 v178, v11, v11
	v_fmac_f32_e32 v178, v250, v250
	v_fmac_f32_e32 v178, v12, v12
	v_fmac_f32_e32 v178, v251, v251
	v_fmac_f32_e32 v178, v13, v13
	v_fmac_f32_e32 v178, v176, v176
	v_fmac_f32_e32 v178, v14, v14
	v_fmac_f32_e32 v178, v177, v177
	v_fmac_f32_e32 v178, v15, v15
	s_waitcnt vmcnt(48)
	v_lshlrev_b32_e32 v238, 16, v16
	v_and_b32_e32 v16, 0xffff0000, v16
	v_add_f32_dpp v178, v178, v178 quad_perm:[1,0,3,2] row_mask:0xf bank_mask:0xf bound_ctrl:1
	v_lshlrev_b32_e32 v239, 16, v17
	v_and_b32_e32 v17, 0xffff0000, v17
	v_add_f32_dpp v178, v178, v178 quad_perm:[2,3,0,1] row_mask:0xf bank_mask:0xf bound_ctrl:1
	v_lshlrev_b32_e32 v240, 16, v18
	v_and_b32_e32 v18, 0xffff0000, v18
	v_add_f32_dpp v178, v178, v178 row_half_mirror row_mask:0xf bank_mask:0xf bound_ctrl:1
	v_lshlrev_b32_e32 v241, 16, v19
	v_and_b32_e32 v19, 0xffff0000, v19
	v_add_f32_dpp v178, v178, v178 row_mirror row_mask:0xf bank_mask:0xf bound_ctrl:1
	v_lshlrev_b32_e32 v242, 16, v20
	v_and_b32_e32 v20, 0xffff0000, v20
	v_add_f32_dpp v178, v178, v178 row_bcast:15 row_mask:0xa bank_mask:0xf
	v_lshlrev_b32_e32 v243, 16, v21
	v_and_b32_e32 v21, 0xffff0000, v21
	v_add_f32_dpp v178, v178, v178 row_bcast:31 row_mask:0xc bank_mask:0xf
	v_lshlrev_b32_e32 v244, 16, v22
	v_and_b32_e32 v22, 0xffff0000, v22
	v_lshlrev_b32_e32 v245, 16, v23
	v_and_b32_e32 v23, 0xffff0000, v23
	v_readlane_b32 s0, v178, 63
	s_nop 1
	v_mov_b32_e32 v181, s0
	v_fmamk_f32 v181, v181, 0x3a800000, v161
	v_rsq_f32_e32 v179, v181
	s_nop 0
	s_waitcnt vmcnt(40)
	v_mul_f32_e32 v246, v246, v179
	v_mul_f32_e32 v8, v8, v179
	v_mul_f32_e32 v247, v247, v179
	v_mul_f32_e32 v9, v9, v179
	v_mul_f32_e32 v248, v248, v179
	v_mul_f32_e32 v10, v10, v179
	v_mul_f32_e32 v249, v249, v179
	v_mul_f32_e32 v11, v11, v179
	v_mul_f32_e32 v250, v250, v179
	v_mul_f32_e32 v12, v12, v179
	v_mul_f32_e32 v251, v251, v179
	v_mul_f32_e32 v13, v13, v179
	v_mul_f32_e32 v176, v176, v179
	v_mul_f32_e32 v14, v14, v179
	v_mul_f32_e32 v177, v177, v179
	v_mul_f32_e32 v15, v15, v179
	v_mul_f32_e32 v246, v246, v56
	v_mul_f32_e32 v8, v8, v57
	v_mul_f32_e32 v247, v247, v58
	v_mul_f32_e32 v9, v9, v59
	v_mul_f32_e32 v248, v248, v60
	v_mul_f32_e32 v10, v10, v61
	v_mul_f32_e32 v249, v249, v62
	v_mul_f32_e32 v11, v11, v63
	v_mul_f32_e32 v250, v250, v64
	v_mul_f32_e32 v12, v12, v65
	v_mul_f32_e32 v251, v251, v66
	v_mul_f32_e32 v13, v13, v67
	v_mul_f32_e32 v176, v176, v68
	v_mul_f32_e32 v14, v14, v69
	v_mul_f32_e32 v177, v177, v70
	v_mul_f32_e32 v15, v15, v71
	v_fmac_f32_e32 v238, v190, v246
	v_fmac_f32_e32 v16, v191, v8
	v_fmac_f32_e32 v239, v192, v247
	v_fmac_f32_e32 v17, v193, v9
	v_fmac_f32_e32 v240, v194, v248
	v_fmac_f32_e32 v18, v195, v10
	v_fmac_f32_e32 v241, v196, v249
	v_fmac_f32_e32 v19, v197, v11
	v_fmac_f32_e32 v242, v198, v250
	v_fmac_f32_e32 v20, v199, v12
	v_fmac_f32_e32 v243, v200, v251
	v_fmac_f32_e32 v21, v201, v13
	v_fmac_f32_e32 v244, v202, v176
	v_fmac_f32_e32 v22, v203, v14
	v_fmac_f32_e32 v245, v204, v177
	v_fmac_f32_e32 v23, v205, v15
	v_cvt_pk_bf16_f32 v120, v238, v16
	v_cvt_pk_bf16_f32 v121, v239, v17
	global_store_dwordx2 v5, v[120:121], s[4:5] offset:0 nt
	v_cvt_pk_bf16_f32 v122, v240, v18
	v_cvt_pk_bf16_f32 v123, v241, v19
	global_store_dwordx2 v5, v[122:123], s[4:5] offset:512 nt
	v_cvt_pk_bf16_f32 v124, v242, v20
	v_cvt_pk_bf16_f32 v125, v243, v21
	global_store_dwordx2 v5, v[124:125], s[4:5] offset:1024 nt
	v_cvt_pk_bf16_f32 v126, v244, v22
	v_cvt_pk_bf16_f32 v127, v245, v23
	global_store_dwordx2 v5, v[126:127], s[4:5] offset:1536 nt
	v_mul_f32_e32 v178, v238, v238
	v_fmac_f32_e32 v178, v16, v16
	v_fmac_f32_e32 v178, v239, v239
	v_fmac_f32_e32 v178, v17, v17
	v_fmac_f32_e32 v178, v240, v240
	v_fmac_f32_e32 v178, v18, v18
	v_fmac_f32_e32 v178, v241, v241
	v_fmac_f32_e32 v178, v19, v19
	v_fmac_f32_e32 v178, v242, v242
	v_fmac_f32_e32 v178, v20, v20
	v_fmac_f32_e32 v178, v243, v243
	v_fmac_f32_e32 v178, v21, v21
	v_fmac_f32_e32 v178, v244, v244
	v_fmac_f32_e32 v178, v22, v22
	v_fmac_f32_e32 v178, v245, v245
	v_fmac_f32_e32 v178, v23, v23
	s_waitcnt vmcnt(36)
	v_add_f32_e32 v206, 1.0, v206
	v_add_f32_e32 v207, 1.0, v207
	v_add_f32_dpp v178, v178, v178 quad_perm:[1,0,3,2] row_mask:0xf bank_mask:0xf bound_ctrl:1
	v_add_f32_e32 v208, 1.0, v208
	v_add_f32_e32 v209, 1.0, v209
	v_add_f32_dpp v178, v178, v178 quad_perm:[2,3,0,1] row_mask:0xf bank_mask:0xf bound_ctrl:1
	v_add_f32_e32 v210, 1.0, v210
	v_add_f32_e32 v211, 1.0, v211
	v_add_f32_dpp v178, v178, v178 row_half_mirror row_mask:0xf bank_mask:0xf bound_ctrl:1
	v_add_f32_e32 v212, 1.0, v212
	v_add_f32_e32 v213, 1.0, v213
	v_add_f32_dpp v178, v178, v178 row_mirror row_mask:0xf bank_mask:0xf bound_ctrl:1
	v_add_f32_e32 v214, 1.0, v214
	v_add_f32_e32 v215, 1.0, v215
	v_add_f32_dpp v178, v178, v178 row_bcast:15 row_mask:0xa bank_mask:0xf
	v_add_f32_e32 v216, 1.0, v216
	v_add_f32_e32 v217, 1.0, v217
	v_add_f32_dpp v178, v178, v178 row_bcast:31 row_mask:0xc bank_mask:0xf
	v_add_f32_e32 v218, 1.0, v218
	v_add_f32_e32 v219, 1.0, v219
	v_add_f32_e32 v220, 1.0, v220
	v_add_f32_e32 v221, 1.0, v221
	v_readlane_b32 s0, v178, 63
	s_nop 1
	v_mov_b32_e32 v181, s0
	v_fmamk_f32 v181, v181, 0x3a800000, v161
	v_rsq_f32_e32 v180, v181
	s_nop 0
	s_waitcnt vmcnt(32)
	v_mul_f32_e32 v238, v238, v180
	v_mul_f32_e32 v16, v16, v180
	v_mul_f32_e32 v239, v239, v180
	v_mul_f32_e32 v17, v17, v180
	v_mul_f32_e32 v240, v240, v180
	v_mul_f32_e32 v18, v18, v180
	v_mul_f32_e32 v241, v241, v180
	v_mul_f32_e32 v19, v19, v180
	v_mul_f32_e32 v242, v242, v180
	v_mul_f32_e32 v20, v20, v180
	v_mul_f32_e32 v243, v243, v180
	v_mul_f32_e32 v21, v21, v180
	v_mul_f32_e32 v244, v244, v180
	v_mul_f32_e32 v22, v22, v180
	v_mul_f32_e32 v245, v245, v180
	v_mul_f32_e32 v23, v23, v180
	v_mul_f32_e32 v238, v238, v72
	v_mul_f32_e32 v16, v16, v73
	v_mul_f32_e32 v239, v239, v74
	v_mul_f32_e32 v17, v17, v75
	v_mul_f32_e32 v240, v240, v76
	v_mul_f32_e32 v18, v18, v77
	v_mul_f32_e32 v241, v241, v78
	v_mul_f32_e32 v19, v19, v79
	v_mul_f32_e32 v242, v242, v80
	v_mul_f32_e32 v20, v20, v81
	v_mul_f32_e32 v243, v243, v82
	v_mul_f32_e32 v21, v21, v83
	v_mul_f32_e32 v244, v244, v84
	v_mul_f32_e32 v22, v22, v85
	v_mul_f32_e32 v245, v245, v86
	v_mul_f32_e32 v23, v23, v87
	v_fma_f32 v238, v238, v206, v222
	v_fma_f32 v16, v16, v207, v223
	v_fma_f32 v239, v239, v208, v224
	v_fma_f32 v17, v17, v209, v225
	v_fma_f32 v240, v240, v210, v226
	v_fma_f32 v18, v18, v211, v227
	v_fma_f32 v241, v241, v212, v228
	v_fma_f32 v19, v19, v213, v229
	v_fma_f32 v242, v242, v214, v230
	v_fma_f32 v20, v20, v215, v231
	v_fma_f32 v243, v243, v216, v232
	v_fma_f32 v21, v21, v217, v233
	v_fma_f32 v244, v244, v218, v234
	v_fma_f32 v22, v22, v219, v235
	v_fma_f32 v245, v245, v220, v236
	v_fma_f32 v23, v23, v221, v237
	v_cvt_pk_bf16_f32 v150, v238, v16
	v_cvt_pk_bf16_f32 v151, v239, v17
	global_store_dwordx2 v5, v[150:151], s[8:9] offset:0
	v_cvt_pk_bf16_f32 v152, v240, v18
	v_cvt_pk_bf16_f32 v153, v241, v19
	global_store_dwordx2 v5, v[152:153], s[8:9] offset:512
	v_cvt_pk_bf16_f32 v154, v242, v20
	v_cvt_pk_bf16_f32 v155, v243, v21
	global_store_dwordx2 v5, v[154:155], s[8:9] offset:1024
	v_cvt_pk_bf16_f32 v156, v244, v22
	v_cvt_pk_bf16_f32 v157, v245, v23
	global_store_dwordx2 v5, v[156:157], s[8:9] offset:1536
	global_load_dwordx2 v[8:9], v3, s[6:7] offset:0 nt
	global_load_dwordx2 v[10:11], v3, s[6:7] offset:512 nt
	global_load_dwordx2 v[12:13], v3, s[6:7] offset:1024 nt
	global_load_dwordx2 v[14:15], v3, s[6:7] offset:1536 nt
	global_load_dwordx2 v[16:17], v3, s[4:5] offset:0 nt
	global_load_dwordx2 v[18:19], v3, s[4:5] offset:512 nt
	global_load_dwordx2 v[20:21], v3, s[4:5] offset:1024 nt
	global_load_dwordx2 v[22:23], v3, s[4:5] offset:1536 nt
	global_load_dwordx2 v[190:191], v4, s[6:7] offset:0 nt
	global_load_dwordx2 v[192:193], v4, s[6:7] offset:512 nt
	global_load_dwordx2 v[194:195], v4, s[6:7] offset:1024 nt
	global_load_dwordx2 v[196:197], v4, s[6:7] offset:1536 nt
	global_load_dwordx2 v[198:199], v4, s[4:5] offset:0 nt
	global_load_dwordx2 v[200:201], v4, s[4:5] offset:512 nt
	global_load_dwordx2 v[202:203], v4, s[4:5] offset:1024 nt
	global_load_dwordx2 v[204:205], v4, s[4:5] offset:1536 nt
	s_waitcnt vmcnt(48)
	v_lshlrev_b32_e32 v246, 16, v24
	v_and_b32_e32 v24, 0xffff0000, v24
	v_lshlrev_b32_e32 v247, 16, v25
	v_and_b32_e32 v25, 0xffff0000, v25
	v_lshlrev_b32_e32 v248, 16, v26
	v_and_b32_e32 v26, 0xffff0000, v26
	v_lshlrev_b32_e32 v249, 16, v27
	v_and_b32_e32 v27, 0xffff0000, v27
	v_lshlrev_b32_e32 v250, 16, v28
	v_and_b32_e32 v28, 0xffff0000, v28
	v_lshlrev_b32_e32 v251, 16, v29
	v_and_b32_e32 v29, 0xffff0000, v29
	v_lshlrev_b32_e32 v176, 16, v30
	v_and_b32_e32 v30, 0xffff0000, v30
	v_lshlrev_b32_e32 v177, 16, v31
	v_and_b32_e32 v31, 0xffff0000, v31
	v_mul_f32_e32 v178, v246, v246
	v_fmac_f32_e32 v178, v24, v24
	v_fmac_f32_e32 v178, v247, v247
	v_fmac_f32_e32 v178, v25, v25
	v_fmac_f32_e32 v178, v248, v248
	v_fmac_f32_e32 v178, v26, v26
	v_fmac_f32_e32 v178, v249, v249
	v_fmac_f32_e32 v178, v27, v27
	v_fmac_f32_e32 v178, v250, v250
	v_fmac_f32_e32 v178, v28, v28
	v_fmac_f32_e32 v178, v251, v251
	v_fmac_f32_e32 v178, v29, v29
	v_fmac_f32_e32 v178, v176, v176
	v_fmac_f32_e32 v178, v30, v30
	v_fmac_f32_e32 v178, v177, v177
	v_fmac_f32_e32 v178, v31, v31
	s_waitcnt vmcnt(44)
	v_lshlrev_b32_e32 v238, 16, v32
	v_and_b32_e32 v32, 0xffff0000, v32
	v_add_f32_dpp v178, v178, v178 quad_perm:[1,0,3,2] row_mask:0xf bank_mask:0xf bound_ctrl:1
	v_lshlrev_b32_e32 v239, 16, v33
	v_and_b32_e32 v33, 0xffff0000, v33
	v_add_f32_dpp v178, v178, v178 quad_perm:[2,3,0,1] row_mask:0xf bank_mask:0xf bound_ctrl:1
	v_lshlrev_b32_e32 v240, 16, v34
	v_and_b32_e32 v34, 0xffff0000, v34
	v_add_f32_dpp v178, v178, v178 row_half_mirror row_mask:0xf bank_mask:0xf bound_ctrl:1
	v_lshlrev_b32_e32 v241, 16, v35
	v_and_b32_e32 v35, 0xffff0000, v35
	v_add_f32_dpp v178, v178, v178 row_mirror row_mask:0xf bank_mask:0xf bound_ctrl:1
	v_lshlrev_b32_e32 v242, 16, v36
	v_and_b32_e32 v36, 0xffff0000, v36
	v_add_f32_dpp v178, v178, v178 row_bcast:15 row_mask:0xa bank_mask:0xf
	v_lshlrev_b32_e32 v243, 16, v37
	v_and_b32_e32 v37, 0xffff0000, v37
	v_add_f32_dpp v178, v178, v178 row_bcast:31 row_mask:0xc bank_mask:0xf
	v_lshlrev_b32_e32 v244, 16, v38
	v_and_b32_e32 v38, 0xffff0000, v38
	v_lshlrev_b32_e32 v245, 16, v39
	v_and_b32_e32 v39, 0xffff0000, v39
	v_readlane_b32 s0, v178, 63
	s_nop 1
	v_mov_b32_e32 v181, s0
	v_fmamk_f32 v181, v181, 0x3a800000, v161
	v_rsq_f32_e32 v179, v181
	s_nop 0
	s_waitcnt vmcnt(40)
	v_mul_f32_e32 v246, v246, v179
	v_mul_f32_e32 v24, v24, v179
	v_mul_f32_e32 v247, v247, v179
	v_mul_f32_e32 v25, v25, v179
	v_mul_f32_e32 v248, v248, v179
	v_mul_f32_e32 v26, v26, v179
	v_mul_f32_e32 v249, v249, v179
	v_mul_f32_e32 v27, v27, v179
	v_mul_f32_e32 v250, v250, v179
	v_mul_f32_e32 v28, v28, v179
	v_mul_f32_e32 v251, v251, v179
	v_mul_f32_e32 v29, v29, v179
	v_mul_f32_e32 v176, v176, v179
	v_mul_f32_e32 v30, v30, v179
	v_mul_f32_e32 v177, v177, v179
	v_mul_f32_e32 v31, v31, v179
	v_mul_f32_e32 v246, v246, v56
	v_mul_f32_e32 v24, v24, v57
	v_mul_f32_e32 v247, v247, v58
	v_mul_f32_e32 v25, v25, v59
	v_mul_f32_e32 v248, v248, v60
	v_mul_f32_e32 v26, v26, v61
	v_mul_f32_e32 v249, v249, v62
	v_mul_f32_e32 v27, v27, v63
	v_mul_f32_e32 v250, v250, v64
	v_mul_f32_e32 v28, v28, v65
	v_mul_f32_e32 v251, v251, v66
	v_mul_f32_e32 v29, v29, v67
	v_mul_f32_e32 v176, v176, v68
	v_mul_f32_e32 v30, v30, v69
	v_mul_f32_e32 v177, v177, v70
	v_mul_f32_e32 v31, v31, v71
	v_fmac_f32_e32 v238, v88, v246
	v_fmac_f32_e32 v32, v89, v24
	v_fmac_f32_e32 v239, v90, v247
	v_fmac_f32_e32 v33, v91, v25
	v_fmac_f32_e32 v240, v92, v248
	v_fmac_f32_e32 v34, v93, v26
	v_fmac_f32_e32 v241, v94, v249
	v_fmac_f32_e32 v35, v95, v27
	v_fmac_f32_e32 v242, v96, v250
	v_fmac_f32_e32 v36, v97, v28
	v_fmac_f32_e32 v243, v98, v251
	v_fmac_f32_e32 v37, v99, v29
	v_fmac_f32_e32 v244, v100, v176
	v_fmac_f32_e32 v38, v101, v30
	v_fmac_f32_e32 v245, v102, v177
	v_fmac_f32_e32 v39, v103, v31
	v_cvt_pk_bf16_f32 v120, v238, v32
	v_cvt_pk_bf16_f32 v121, v239, v33
	global_store_dwordx2 v0, v[120:121], s[4:5] offset:0 nt
	v_cvt_pk_bf16_f32 v122, v240, v34
	v_cvt_pk_bf16_f32 v123, v241, v35
	global_store_dwordx2 v0, v[122:123], s[4:5] offset:512 nt
	v_cvt_pk_bf16_f32 v124, v242, v36
	v_cvt_pk_bf16_f32 v125, v243, v37
	global_store_dwordx2 v0, v[124:125], s[4:5] offset:1024 nt
	v_cvt_pk_bf16_f32 v126, v244, v38
	v_cvt_pk_bf16_f32 v127, v245, v39
	global_store_dwordx2 v0, v[126:127], s[4:5] offset:1536 nt
	v_mul_f32_e32 v178, v238, v238
	v_fmac_f32_e32 v178, v32, v32
	v_fmac_f32_e32 v178, v239, v239
	v_fmac_f32_e32 v178, v33, v33
	v_fmac_f32_e32 v178, v240, v240
	v_fmac_f32_e32 v178, v34, v34
	v_fmac_f32_e32 v178, v241, v241
	v_fmac_f32_e32 v178, v35, v35
	v_fmac_f32_e32 v178, v242, v242
	v_fmac_f32_e32 v178, v36, v36
	v_fmac_f32_e32 v178, v243, v243
	v_fmac_f32_e32 v178, v37, v37
	v_fmac_f32_e32 v178, v244, v244
	v_fmac_f32_e32 v178, v38, v38
	v_fmac_f32_e32 v178, v245, v245
	v_fmac_f32_e32 v178, v39, v39
	s_waitcnt vmcnt(40)
	v_add_f32_e32 v104, 1.0, v104
	v_add_f32_e32 v105, 1.0, v105
	v_add_f32_dpp v178, v178, v178 quad_perm:[1,0,3,2] row_mask:0xf bank_mask:0xf bound_ctrl:1
	v_add_f32_e32 v106, 1.0, v106
	v_add_f32_e32 v107, 1.0, v107
	v_add_f32_dpp v178, v178, v178 quad_perm:[2,3,0,1] row_mask:0xf bank_mask:0xf bound_ctrl:1
	v_add_f32_e32 v108, 1.0, v108
	v_add_f32_e32 v109, 1.0, v109
	v_add_f32_dpp v178, v178, v178 row_half_mirror row_mask:0xf bank_mask:0xf bound_ctrl:1
	v_add_f32_e32 v110, 1.0, v110
	v_add_f32_e32 v111, 1.0, v111
	v_add_f32_dpp v178, v178, v178 row_mirror row_mask:0xf bank_mask:0xf bound_ctrl:1
	v_add_f32_e32 v112, 1.0, v112
	v_add_f32_e32 v113, 1.0, v113
	v_add_f32_dpp v178, v178, v178 row_bcast:15 row_mask:0xa bank_mask:0xf
	v_add_f32_e32 v114, 1.0, v114
	v_add_f32_e32 v115, 1.0, v115
	v_add_f32_dpp v178, v178, v178 row_bcast:31 row_mask:0xc bank_mask:0xf
	v_add_f32_e32 v116, 1.0, v116
	v_add_f32_e32 v117, 1.0, v117
	v_add_f32_e32 v118, 1.0, v118
	v_add_f32_e32 v119, 1.0, v119
	v_readlane_b32 s0, v178, 63
	s_nop 1
	v_mov_b32_e32 v181, s0
	v_fmamk_f32 v181, v181, 0x3a800000, v161
	v_rsq_f32_e32 v180, v181
	s_nop 0
	s_waitcnt vmcnt(36)
	v_mul_f32_e32 v238, v238, v180
	v_mul_f32_e32 v32, v32, v180
	v_mul_f32_e32 v239, v239, v180
	v_mul_f32_e32 v33, v33, v180
	v_mul_f32_e32 v240, v240, v180
	v_mul_f32_e32 v34, v34, v180
	v_mul_f32_e32 v241, v241, v180
	v_mul_f32_e32 v35, v35, v180
	v_mul_f32_e32 v242, v242, v180
	v_mul_f32_e32 v36, v36, v180
	v_mul_f32_e32 v243, v243, v180
	v_mul_f32_e32 v37, v37, v180
	v_mul_f32_e32 v244, v244, v180
	v_mul_f32_e32 v38, v38, v180
	v_mul_f32_e32 v245, v245, v180
	v_mul_f32_e32 v39, v39, v180
	v_mul_f32_e32 v238, v238, v72
	v_mul_f32_e32 v32, v32, v73
	v_mul_f32_e32 v239, v239, v74
	v_mul_f32_e32 v33, v33, v75
	v_mul_f32_e32 v240, v240, v76
	v_mul_f32_e32 v34, v34, v77
	v_mul_f32_e32 v241, v241, v78
	v_mul_f32_e32 v35, v35, v79
	v_mul_f32_e32 v242, v242, v80
	v_mul_f32_e32 v36, v36, v81
	v_mul_f32_e32 v243, v243, v82
	v_mul_f32_e32 v37, v37, v83
	v_mul_f32_e32 v244, v244, v84
	v_mul_f32_e32 v38, v38, v85
	v_mul_f32_e32 v245, v245, v86
	v_mul_f32_e32 v39, v39, v87
	v_fma_f32 v238, v238, v104, v134
	v_fma_f32 v32, v32, v105, v135
	v_fma_f32 v239, v239, v106, v136
	v_fma_f32 v33, v33, v107, v137
	v_fma_f32 v240, v240, v108, v138
	v_fma_f32 v34, v34, v109, v139
	v_fma_f32 v241, v241, v110, v140
	v_fma_f32 v35, v35, v111, v141
	v_fma_f32 v242, v242, v112, v142
	v_fma_f32 v36, v36, v113, v143
	v_fma_f32 v243, v243, v114, v144
	v_fma_f32 v37, v37, v115, v145
	v_fma_f32 v244, v244, v116, v146
	v_fma_f32 v38, v38, v117, v147
	v_fma_f32 v245, v245, v118, v148
	v_fma_f32 v39, v39, v119, v149
	v_cvt_pk_bf16_f32 v150, v238, v32
	v_cvt_pk_bf16_f32 v151, v239, v33
	global_store_dwordx2 v0, v[150:151], s[8:9] offset:0
	v_cvt_pk_bf16_f32 v152, v240, v34
	v_cvt_pk_bf16_f32 v153, v241, v35
	global_store_dwordx2 v0, v[152:153], s[8:9] offset:512
	v_cvt_pk_bf16_f32 v154, v242, v36
	v_cvt_pk_bf16_f32 v155, v243, v37
	global_store_dwordx2 v0, v[154:155], s[8:9] offset:1024
	v_cvt_pk_bf16_f32 v156, v244, v38
	v_cvt_pk_bf16_f32 v157, v245, v39
	global_store_dwordx2 v0, v[156:157], s[8:9] offset:1536
	s_waitcnt vmcnt(36)
	v_lshlrev_b32_e32 v246, 16, v40
	v_and_b32_e32 v40, 0xffff0000, v40
	v_lshlrev_b32_e32 v247, 16, v41
	v_and_b32_e32 v41, 0xffff0000, v41
	v_lshlrev_b32_e32 v248, 16, v42
	v_and_b32_e32 v42, 0xffff0000, v42
	v_lshlrev_b32_e32 v249, 16, v43
	v_and_b32_e32 v43, 0xffff0000, v43
	v_lshlrev_b32_e32 v250, 16, v44
	v_and_b32_e32 v44, 0xffff0000, v44
	v_lshlrev_b32_e32 v251, 16, v45
	v_and_b32_e32 v45, 0xffff0000, v45
	v_lshlrev_b32_e32 v176, 16, v46
	v_and_b32_e32 v46, 0xffff0000, v46
	v_lshlrev_b32_e32 v177, 16, v47
	v_and_b32_e32 v47, 0xffff0000, v47
	v_mul_f32_e32 v178, v246, v246
	v_fmac_f32_e32 v178, v40, v40
	v_fmac_f32_e32 v178, v247, v247
	v_fmac_f32_e32 v178, v41, v41
	v_fmac_f32_e32 v178, v248, v248
	v_fmac_f32_e32 v178, v42, v42
	v_fmac_f32_e32 v178, v249, v249
	v_fmac_f32_e32 v178, v43, v43
	v_fmac_f32_e32 v178, v250, v250
	v_fmac_f32_e32 v178, v44, v44
	v_fmac_f32_e32 v178, v251, v251
	v_fmac_f32_e32 v178, v45, v45
	v_fmac_f32_e32 v178, v176, v176
	v_fmac_f32_e32 v178, v46, v46
	v_fmac_f32_e32 v178, v177, v177
	v_fmac_f32_e32 v178, v47, v47
	s_waitcnt vmcnt(32)
	v_lshlrev_b32_e32 v238, 16, v48
	v_and_b32_e32 v48, 0xffff0000, v48
	v_add_f32_dpp v178, v178, v178 quad_perm:[1,0,3,2] row_mask:0xf bank_mask:0xf bound_ctrl:1
	v_lshlrev_b32_e32 v239, 16, v49
	v_and_b32_e32 v49, 0xffff0000, v49
	v_add_f32_dpp v178, v178, v178 quad_perm:[2,3,0,1] row_mask:0xf bank_mask:0xf bound_ctrl:1
	v_lshlrev_b32_e32 v240, 16, v50
	v_and_b32_e32 v50, 0xffff0000, v50
	v_add_f32_dpp v178, v178, v178 row_half_mirror row_mask:0xf bank_mask:0xf bound_ctrl:1
	v_lshlrev_b32_e32 v241, 16, v51
	v_and_b32_e32 v51, 0xffff0000, v51
	v_add_f32_dpp v178, v178, v178 row_mirror row_mask:0xf bank_mask:0xf bound_ctrl:1
	v_lshlrev_b32_e32 v242, 16, v52
	v_and_b32_e32 v52, 0xffff0000, v52
	v_add_f32_dpp v178, v178, v178 row_bcast:15 row_mask:0xa bank_mask:0xf
	v_lshlrev_b32_e32 v243, 16, v53
	v_and_b32_e32 v53, 0xffff0000, v53
	v_add_f32_dpp v178, v178, v178 row_bcast:31 row_mask:0xc bank_mask:0xf
	v_lshlrev_b32_e32 v244, 16, v54
	v_and_b32_e32 v54, 0xffff0000, v54
	v_lshlrev_b32_e32 v245, 16, v55
	v_and_b32_e32 v55, 0xffff0000, v55
	v_readlane_b32 s0, v178, 63
	s_nop 1
	v_mov_b32_e32 v181, s0
	v_fmamk_f32 v181, v181, 0x3a800000, v161
	v_rsq_f32_e32 v179, v181
	s_nop 0
	v_mul_f32_e32 v246, v246, v179
	v_mul_f32_e32 v40, v40, v179
	v_mul_f32_e32 v247, v247, v179
	v_mul_f32_e32 v41, v41, v179
	v_mul_f32_e32 v248, v248, v179
	v_mul_f32_e32 v42, v42, v179
	v_mul_f32_e32 v249, v249, v179
	v_mul_f32_e32 v43, v43, v179
	v_mul_f32_e32 v250, v250, v179
	v_mul_f32_e32 v44, v44, v179
	v_mul_f32_e32 v251, v251, v179
	v_mul_f32_e32 v45, v45, v179
	v_mul_f32_e32 v176, v176, v179
	v_mul_f32_e32 v46, v46, v179
	v_mul_f32_e32 v177, v177, v179
	v_mul_f32_e32 v47, v47, v179
	v_mul_f32_e32 v246, v246, v56
	v_mul_f32_e32 v40, v40, v57
	v_mul_f32_e32 v247, v247, v58
	v_mul_f32_e32 v41, v41, v59
	v_mul_f32_e32 v248, v248, v60
	v_mul_f32_e32 v42, v42, v61
	v_mul_f32_e32 v249, v249, v62
	v_mul_f32_e32 v43, v43, v63
	v_mul_f32_e32 v250, v250, v64
	v_mul_f32_e32 v44, v44, v65
	v_mul_f32_e32 v251, v251, v66
	v_mul_f32_e32 v45, v45, v67
	v_mul_f32_e32 v176, v176, v68
	v_mul_f32_e32 v46, v46, v69
	v_mul_f32_e32 v177, v177, v70
	v_mul_f32_e32 v47, v47, v71
	v_fmac_f32_e32 v238, v88, v246
	v_fmac_f32_e32 v48, v89, v40
	v_fmac_f32_e32 v239, v90, v247
	v_fmac_f32_e32 v49, v91, v41
	v_fmac_f32_e32 v240, v92, v248
	v_fmac_f32_e32 v50, v93, v42
	v_fmac_f32_e32 v241, v94, v249
	v_fmac_f32_e32 v51, v95, v43
	v_fmac_f32_e32 v242, v96, v250
	v_fmac_f32_e32 v52, v97, v44
	v_fmac_f32_e32 v243, v98, v251
	v_fmac_f32_e32 v53, v99, v45
	v_fmac_f32_e32 v244, v100, v176
	v_fmac_f32_e32 v54, v101, v46
	v_fmac_f32_e32 v245, v102, v177
	v_fmac_f32_e32 v55, v103, v47
	v_cvt_pk_bf16_f32 v120, v238, v48
	v_cvt_pk_bf16_f32 v121, v239, v49
	global_store_dwordx2 v2, v[120:121], s[4:5] offset:0 nt
	v_cvt_pk_bf16_f32 v122, v240, v50
	v_cvt_pk_bf16_f32 v123, v241, v51
	global_store_dwordx2 v2, v[122:123], s[4:5] offset:512 nt
	v_cvt_pk_bf16_f32 v124, v242, v52
	v_cvt_pk_bf16_f32 v125, v243, v53
	global_store_dwordx2 v2, v[124:125], s[4:5] offset:1024 nt
	v_cvt_pk_bf16_f32 v126, v244, v54
	v_cvt_pk_bf16_f32 v127, v245, v55
	global_store_dwordx2 v2, v[126:127], s[4:5] offset:1536 nt
	v_mul_f32_e32 v178, v238, v238
	v_fmac_f32_e32 v178, v48, v48
	v_fmac_f32_e32 v178, v239, v239
	v_fmac_f32_e32 v178, v49, v49
	v_fmac_f32_e32 v178, v240, v240
	v_fmac_f32_e32 v178, v50, v50
	v_fmac_f32_e32 v178, v241, v241
	v_fmac_f32_e32 v178, v51, v51
	v_fmac_f32_e32 v178, v242, v242
	v_fmac_f32_e32 v178, v52, v52
	v_fmac_f32_e32 v178, v243, v243
	v_fmac_f32_e32 v178, v53, v53
	v_fmac_f32_e32 v178, v244, v244
	v_fmac_f32_e32 v178, v54, v54
	v_fmac_f32_e32 v178, v245, v245
	v_fmac_f32_e32 v178, v55, v55
	s_nop 1
	v_add_f32_dpp v178, v178, v178 quad_perm:[1,0,3,2] row_mask:0xf bank_mask:0xf bound_ctrl:1
	s_nop 1
	v_add_f32_dpp v178, v178, v178 quad_perm:[2,3,0,1] row_mask:0xf bank_mask:0xf bound_ctrl:1
	s_nop 1
	v_add_f32_dpp v178, v178, v178 row_half_mirror row_mask:0xf bank_mask:0xf bound_ctrl:1
	s_nop 1
	v_add_f32_dpp v178, v178, v178 row_mirror row_mask:0xf bank_mask:0xf bound_ctrl:1
	s_nop 1
	v_add_f32_dpp v178, v178, v178 row_bcast:15 row_mask:0xa bank_mask:0xf
	s_nop 1
	v_add_f32_dpp v178, v178, v178 row_bcast:31 row_mask:0xc bank_mask:0xf
	s_nop 0
	v_readlane_b32 s0, v178, 63
	s_nop 1
	v_mov_b32_e32 v181, s0
	v_fmamk_f32 v181, v181, 0x3a800000, v161
	v_rsq_f32_e32 v180, v181
	s_nop 0
	v_mul_f32_e32 v238, v238, v180
	v_mul_f32_e32 v48, v48, v180
	v_mul_f32_e32 v239, v239, v180
	v_mul_f32_e32 v49, v49, v180
	v_mul_f32_e32 v240, v240, v180
	v_mul_f32_e32 v50, v50, v180
	v_mul_f32_e32 v241, v241, v180
	v_mul_f32_e32 v51, v51, v180
	v_mul_f32_e32 v242, v242, v180
	v_mul_f32_e32 v52, v52, v180
	v_mul_f32_e32 v243, v243, v180
	v_mul_f32_e32 v53, v53, v180
	v_mul_f32_e32 v244, v244, v180
	v_mul_f32_e32 v54, v54, v180
	v_mul_f32_e32 v245, v245, v180
	v_mul_f32_e32 v55, v55, v180
	v_mul_f32_e32 v238, v238, v72
	v_mul_f32_e32 v48, v48, v73
	v_mul_f32_e32 v239, v239, v74
	v_mul_f32_e32 v49, v49, v75
	v_mul_f32_e32 v240, v240, v76
	v_mul_f32_e32 v50, v50, v77
	v_mul_f32_e32 v241, v241, v78
	v_mul_f32_e32 v51, v51, v79
	v_mul_f32_e32 v242, v242, v80
	v_mul_f32_e32 v52, v52, v81
	v_mul_f32_e32 v243, v243, v82
	v_mul_f32_e32 v53, v53, v83
	v_mul_f32_e32 v244, v244, v84
	v_mul_f32_e32 v54, v54, v85
	v_mul_f32_e32 v245, v245, v86
	v_mul_f32_e32 v55, v55, v87
	v_fma_f32 v238, v238, v104, v134
	v_fma_f32 v48, v48, v105, v135
	v_fma_f32 v239, v239, v106, v136
	v_fma_f32 v49, v49, v107, v137
	v_fma_f32 v240, v240, v108, v138
	v_fma_f32 v50, v50, v109, v139
	v_fma_f32 v241, v241, v110, v140
	v_fma_f32 v51, v51, v111, v141
	v_fma_f32 v242, v242, v112, v142
	v_fma_f32 v52, v52, v113, v143
	v_fma_f32 v243, v243, v114, v144
	v_fma_f32 v53, v53, v115, v145
	v_fma_f32 v244, v244, v116, v146
	v_fma_f32 v54, v54, v117, v147
	v_fma_f32 v245, v245, v118, v148
	v_fma_f32 v55, v55, v119, v149
	v_cvt_pk_bf16_f32 v150, v238, v48
	v_cvt_pk_bf16_f32 v151, v239, v49
	global_store_dwordx2 v2, v[150:151], s[8:9] offset:0
	v_cvt_pk_bf16_f32 v152, v240, v50
	v_cvt_pk_bf16_f32 v153, v241, v51
	global_store_dwordx2 v2, v[152:153], s[8:9] offset:512
	v_cvt_pk_bf16_f32 v154, v242, v52
	v_cvt_pk_bf16_f32 v155, v243, v53
	global_store_dwordx2 v2, v[154:155], s[8:9] offset:1024
	v_cvt_pk_bf16_f32 v156, v244, v54
	v_cvt_pk_bf16_f32 v157, v245, v55
	global_store_dwordx2 v2, v[156:157], s[8:9] offset:1536
	s_waitcnt vmcnt(28)
	v_lshlrev_b32_e32 v246, 16, v8
	v_and_b32_e32 v8, 0xffff0000, v8
	v_lshlrev_b32_e32 v247, 16, v9
	v_and_b32_e32 v9, 0xffff0000, v9
	v_lshlrev_b32_e32 v248, 16, v10
	v_and_b32_e32 v10, 0xffff0000, v10
	v_lshlrev_b32_e32 v249, 16, v11
	v_and_b32_e32 v11, 0xffff0000, v11
	v_lshlrev_b32_e32 v250, 16, v12
	v_and_b32_e32 v12, 0xffff0000, v12
	v_lshlrev_b32_e32 v251, 16, v13
	v_and_b32_e32 v13, 0xffff0000, v13
	v_lshlrev_b32_e32 v176, 16, v14
	v_and_b32_e32 v14, 0xffff0000, v14
	v_lshlrev_b32_e32 v177, 16, v15
	v_and_b32_e32 v15, 0xffff0000, v15
	v_mul_f32_e32 v178, v246, v246
	v_fmac_f32_e32 v178, v8, v8
	v_fmac_f32_e32 v178, v247, v247
	v_fmac_f32_e32 v178, v9, v9
	v_fmac_f32_e32 v178, v248, v248
	v_fmac_f32_e32 v178, v10, v10
	v_fmac_f32_e32 v178, v249, v249
	v_fmac_f32_e32 v178, v11, v11
	v_fmac_f32_e32 v178, v250, v250
	v_fmac_f32_e32 v178, v12, v12
	v_fmac_f32_e32 v178, v251, v251
	v_fmac_f32_e32 v178, v13, v13
	v_fmac_f32_e32 v178, v176, v176
	v_fmac_f32_e32 v178, v14, v14
	v_fmac_f32_e32 v178, v177, v177
	v_fmac_f32_e32 v178, v15, v15
	s_waitcnt vmcnt(24)
	v_lshlrev_b32_e32 v238, 16, v16
	v_and_b32_e32 v16, 0xffff0000, v16
	v_add_f32_dpp v178, v178, v178 quad_perm:[1,0,3,2] row_mask:0xf bank_mask:0xf bound_ctrl:1
	v_lshlrev_b32_e32 v239, 16, v17
	v_and_b32_e32 v17, 0xffff0000, v17
	v_add_f32_dpp v178, v178, v178 quad_perm:[2,3,0,1] row_mask:0xf bank_mask:0xf bound_ctrl:1
	v_lshlrev_b32_e32 v240, 16, v18
	v_and_b32_e32 v18, 0xffff0000, v18
	v_add_f32_dpp v178, v178, v178 row_half_mirror row_mask:0xf bank_mask:0xf bound_ctrl:1
	v_lshlrev_b32_e32 v241, 16, v19
	v_and_b32_e32 v19, 0xffff0000, v19
	v_add_f32_dpp v178, v178, v178 row_mirror row_mask:0xf bank_mask:0xf bound_ctrl:1
	v_lshlrev_b32_e32 v242, 16, v20
	v_and_b32_e32 v20, 0xffff0000, v20
	v_add_f32_dpp v178, v178, v178 row_bcast:15 row_mask:0xa bank_mask:0xf
	v_lshlrev_b32_e32 v243, 16, v21
	v_and_b32_e32 v21, 0xffff0000, v21
	v_add_f32_dpp v178, v178, v178 row_bcast:31 row_mask:0xc bank_mask:0xf
	v_lshlrev_b32_e32 v244, 16, v22
	v_and_b32_e32 v22, 0xffff0000, v22
	v_lshlrev_b32_e32 v245, 16, v23
	v_and_b32_e32 v23, 0xffff0000, v23
	v_readlane_b32 s0, v178, 63
	s_nop 1
	v_mov_b32_e32 v181, s0
	v_fmamk_f32 v181, v181, 0x3a800000, v161
	v_rsq_f32_e32 v179, v181
	s_nop 0
	v_mul_f32_e32 v246, v246, v179
	v_mul_f32_e32 v8, v8, v179
	v_mul_f32_e32 v247, v247, v179
	v_mul_f32_e32 v9, v9, v179
	v_mul_f32_e32 v248, v248, v179
	v_mul_f32_e32 v10, v10, v179
	v_mul_f32_e32 v249, v249, v179
	v_mul_f32_e32 v11, v11, v179
	v_mul_f32_e32 v250, v250, v179
	v_mul_f32_e32 v12, v12, v179
	v_mul_f32_e32 v251, v251, v179
	v_mul_f32_e32 v13, v13, v179
	v_mul_f32_e32 v176, v176, v179
	v_mul_f32_e32 v14, v14, v179
	v_mul_f32_e32 v177, v177, v179
	v_mul_f32_e32 v15, v15, v179
	v_mul_f32_e32 v246, v246, v56
	v_mul_f32_e32 v8, v8, v57
	v_mul_f32_e32 v247, v247, v58
	v_mul_f32_e32 v9, v9, v59
	v_mul_f32_e32 v248, v248, v60
	v_mul_f32_e32 v10, v10, v61
	v_mul_f32_e32 v249, v249, v62
	v_mul_f32_e32 v11, v11, v63
	v_mul_f32_e32 v250, v250, v64
	v_mul_f32_e32 v12, v12, v65
	v_mul_f32_e32 v251, v251, v66
	v_mul_f32_e32 v13, v13, v67
	v_mul_f32_e32 v176, v176, v68
	v_mul_f32_e32 v14, v14, v69
	v_mul_f32_e32 v177, v177, v70
	v_mul_f32_e32 v15, v15, v71
	v_fmac_f32_e32 v238, v88, v246
	v_fmac_f32_e32 v16, v89, v8
	v_fmac_f32_e32 v239, v90, v247
	v_fmac_f32_e32 v17, v91, v9
	v_fmac_f32_e32 v240, v92, v248
	v_fmac_f32_e32 v18, v93, v10
	v_fmac_f32_e32 v241, v94, v249
	v_fmac_f32_e32 v19, v95, v11
	v_fmac_f32_e32 v242, v96, v250
	v_fmac_f32_e32 v20, v97, v12
	v_fmac_f32_e32 v243, v98, v251
	v_fmac_f32_e32 v21, v99, v13
	v_fmac_f32_e32 v244, v100, v176
	v_fmac_f32_e32 v22, v101, v14
	v_fmac_f32_e32 v245, v102, v177
	v_fmac_f32_e32 v23, v103, v15
	v_cvt_pk_bf16_f32 v120, v238, v16
	v_cvt_pk_bf16_f32 v121, v239, v17
	global_store_dwordx2 v3, v[120:121], s[4:5] offset:0 nt
	v_cvt_pk_bf16_f32 v122, v240, v18
	v_cvt_pk_bf16_f32 v123, v241, v19
	global_store_dwordx2 v3, v[122:123], s[4:5] offset:512 nt
	v_cvt_pk_bf16_f32 v124, v242, v20
	v_cvt_pk_bf16_f32 v125, v243, v21
	global_store_dwordx2 v3, v[124:125], s[4:5] offset:1024 nt
	v_cvt_pk_bf16_f32 v126, v244, v22
	v_cvt_pk_bf16_f32 v127, v245, v23
	global_store_dwordx2 v3, v[126:127], s[4:5] offset:1536 nt
	v_mul_f32_e32 v178, v238, v238
	v_fmac_f32_e32 v178, v16, v16
	v_fmac_f32_e32 v178, v239, v239
	v_fmac_f32_e32 v178, v17, v17
	v_fmac_f32_e32 v178, v240, v240
	v_fmac_f32_e32 v178, v18, v18
	v_fmac_f32_e32 v178, v241, v241
	v_fmac_f32_e32 v178, v19, v19
	v_fmac_f32_e32 v178, v242, v242
	v_fmac_f32_e32 v178, v20, v20
	v_fmac_f32_e32 v178, v243, v243
	v_fmac_f32_e32 v178, v21, v21
	v_fmac_f32_e32 v178, v244, v244
	v_fmac_f32_e32 v178, v22, v22
	v_fmac_f32_e32 v178, v245, v245
	v_fmac_f32_e32 v178, v23, v23
	s_nop 1
	v_add_f32_dpp v178, v178, v178 quad_perm:[1,0,3,2] row_mask:0xf bank_mask:0xf bound_ctrl:1
	s_nop 1
	v_add_f32_dpp v178, v178, v178 quad_perm:[2,3,0,1] row_mask:0xf bank_mask:0xf bound_ctrl:1
	s_nop 1
	v_add_f32_dpp v178, v178, v178 row_half_mirror row_mask:0xf bank_mask:0xf bound_ctrl:1
	s_nop 1
	v_add_f32_dpp v178, v178, v178 row_mirror row_mask:0xf bank_mask:0xf bound_ctrl:1
	s_nop 1
	v_add_f32_dpp v178, v178, v178 row_bcast:15 row_mask:0xa bank_mask:0xf
	s_nop 1
	v_add_f32_dpp v178, v178, v178 row_bcast:31 row_mask:0xc bank_mask:0xf
	s_nop 0
	v_readlane_b32 s0, v178, 63
	s_nop 1
	v_mov_b32_e32 v181, s0
	v_fmamk_f32 v181, v181, 0x3a800000, v161
	v_rsq_f32_e32 v180, v181
	s_nop 0
	v_mul_f32_e32 v238, v238, v180
	v_mul_f32_e32 v16, v16, v180
	v_mul_f32_e32 v239, v239, v180
	v_mul_f32_e32 v17, v17, v180
	v_mul_f32_e32 v240, v240, v180
	v_mul_f32_e32 v18, v18, v180
	v_mul_f32_e32 v241, v241, v180
	v_mul_f32_e32 v19, v19, v180
	v_mul_f32_e32 v242, v242, v180
	v_mul_f32_e32 v20, v20, v180
	v_mul_f32_e32 v243, v243, v180
	v_mul_f32_e32 v21, v21, v180
	v_mul_f32_e32 v244, v244, v180
	v_mul_f32_e32 v22, v22, v180
	v_mul_f32_e32 v245, v245, v180
	v_mul_f32_e32 v23, v23, v180
	v_mul_f32_e32 v238, v238, v72
	v_mul_f32_e32 v16, v16, v73
	v_mul_f32_e32 v239, v239, v74
	v_mul_f32_e32 v17, v17, v75
	v_mul_f32_e32 v240, v240, v76
	v_mul_f32_e32 v18, v18, v77
	v_mul_f32_e32 v241, v241, v78
	v_mul_f32_e32 v19, v19, v79
	v_mul_f32_e32 v242, v242, v80
	v_mul_f32_e32 v20, v20, v81
	v_mul_f32_e32 v243, v243, v82
	v_mul_f32_e32 v21, v21, v83
	v_mul_f32_e32 v244, v244, v84
	v_mul_f32_e32 v22, v22, v85
	v_mul_f32_e32 v245, v245, v86
	v_mul_f32_e32 v23, v23, v87
	v_fma_f32 v238, v238, v104, v134
	v_fma_f32 v16, v16, v105, v135
	v_fma_f32 v239, v239, v106, v136
	v_fma_f32 v17, v17, v107, v137
	v_fma_f32 v240, v240, v108, v138
	v_fma_f32 v18, v18, v109, v139
	v_fma_f32 v241, v241, v110, v140
	v_fma_f32 v19, v19, v111, v141
	v_fma_f32 v242, v242, v112, v142
	v_fma_f32 v20, v20, v113, v143
	v_fma_f32 v243, v243, v114, v144
	v_fma_f32 v21, v21, v115, v145
	v_fma_f32 v244, v244, v116, v146
	v_fma_f32 v22, v22, v117, v147
	v_fma_f32 v245, v245, v118, v148
	v_fma_f32 v23, v23, v119, v149
	v_cvt_pk_bf16_f32 v150, v238, v16
	v_cvt_pk_bf16_f32 v151, v239, v17
	global_store_dwordx2 v3, v[150:151], s[8:9] offset:0
	v_cvt_pk_bf16_f32 v152, v240, v18
	v_cvt_pk_bf16_f32 v153, v241, v19
	global_store_dwordx2 v3, v[152:153], s[8:9] offset:512
	v_cvt_pk_bf16_f32 v154, v242, v20
	v_cvt_pk_bf16_f32 v155, v243, v21
	global_store_dwordx2 v3, v[154:155], s[8:9] offset:1024
	v_cvt_pk_bf16_f32 v156, v244, v22
	v_cvt_pk_bf16_f32 v157, v245, v23
	global_store_dwordx2 v3, v[156:157], s[8:9] offset:1536
	s_waitcnt vmcnt(28)
	v_lshlrev_b32_e32 v246, 16, v190
	v_and_b32_e32 v190, 0xffff0000, v190
	v_lshlrev_b32_e32 v247, 16, v191
	v_and_b32_e32 v191, 0xffff0000, v191
	v_lshlrev_b32_e32 v248, 16, v192
	v_and_b32_e32 v192, 0xffff0000, v192
	v_lshlrev_b32_e32 v249, 16, v193
	v_and_b32_e32 v193, 0xffff0000, v193
	v_lshlrev_b32_e32 v250, 16, v194
	v_and_b32_e32 v194, 0xffff0000, v194
	v_lshlrev_b32_e32 v251, 16, v195
	v_and_b32_e32 v195, 0xffff0000, v195
	v_lshlrev_b32_e32 v176, 16, v196
	v_and_b32_e32 v196, 0xffff0000, v196
	v_lshlrev_b32_e32 v177, 16, v197
	v_and_b32_e32 v197, 0xffff0000, v197
	v_mul_f32_e32 v178, v246, v246
	v_fmac_f32_e32 v178, v190, v190
	v_fmac_f32_e32 v178, v247, v247
	v_fmac_f32_e32 v178, v191, v191
	v_fmac_f32_e32 v178, v248, v248
	v_fmac_f32_e32 v178, v192, v192
	v_fmac_f32_e32 v178, v249, v249
	v_fmac_f32_e32 v178, v193, v193
	v_fmac_f32_e32 v178, v250, v250
	v_fmac_f32_e32 v178, v194, v194
	v_fmac_f32_e32 v178, v251, v251
	v_fmac_f32_e32 v178, v195, v195
	v_fmac_f32_e32 v178, v176, v176
	v_fmac_f32_e32 v178, v196, v196
	v_fmac_f32_e32 v178, v177, v177
	v_fmac_f32_e32 v178, v197, v197
	s_waitcnt vmcnt(24)
	v_lshlrev_b32_e32 v238, 16, v198
	v_and_b32_e32 v198, 0xffff0000, v198
	v_add_f32_dpp v178, v178, v178 quad_perm:[1,0,3,2] row_mask:0xf bank_mask:0xf bound_ctrl:1
	v_lshlrev_b32_e32 v239, 16, v199
	v_and_b32_e32 v199, 0xffff0000, v199
	v_add_f32_dpp v178, v178, v178 quad_perm:[2,3,0,1] row_mask:0xf bank_mask:0xf bound_ctrl:1
	v_lshlrev_b32_e32 v240, 16, v200
	v_and_b32_e32 v200, 0xffff0000, v200
	v_add_f32_dpp v178, v178, v178 row_half_mirror row_mask:0xf bank_mask:0xf bound_ctrl:1
	v_lshlrev_b32_e32 v241, 16, v201
	v_and_b32_e32 v201, 0xffff0000, v201
	v_add_f32_dpp v178, v178, v178 row_mirror row_mask:0xf bank_mask:0xf bound_ctrl:1
	v_lshlrev_b32_e32 v242, 16, v202
	v_and_b32_e32 v202, 0xffff0000, v202
	v_add_f32_dpp v178, v178, v178 row_bcast:15 row_mask:0xa bank_mask:0xf
	v_lshlrev_b32_e32 v243, 16, v203
	v_and_b32_e32 v203, 0xffff0000, v203
	v_add_f32_dpp v178, v178, v178 row_bcast:31 row_mask:0xc bank_mask:0xf
	v_lshlrev_b32_e32 v244, 16, v204
	v_and_b32_e32 v204, 0xffff0000, v204
	v_lshlrev_b32_e32 v245, 16, v205
	v_and_b32_e32 v205, 0xffff0000, v205
	v_readlane_b32 s0, v178, 63
	s_nop 1
	v_mov_b32_e32 v181, s0
	v_fmamk_f32 v181, v181, 0x3a800000, v161
	v_rsq_f32_e32 v179, v181
	s_nop 0
	v_mul_f32_e32 v246, v246, v179
	v_mul_f32_e32 v190, v190, v179
	v_mul_f32_e32 v247, v247, v179
	v_mul_f32_e32 v191, v191, v179
	v_mul_f32_e32 v248, v248, v179
	v_mul_f32_e32 v192, v192, v179
	v_mul_f32_e32 v249, v249, v179
	v_mul_f32_e32 v193, v193, v179
	v_mul_f32_e32 v250, v250, v179
	v_mul_f32_e32 v194, v194, v179
	v_mul_f32_e32 v251, v251, v179
	v_mul_f32_e32 v195, v195, v179
	v_mul_f32_e32 v176, v176, v179
	v_mul_f32_e32 v196, v196, v179
	v_mul_f32_e32 v177, v177, v179
	v_mul_f32_e32 v197, v197, v179
	v_mul_f32_e32 v246, v246, v56
	v_mul_f32_e32 v190, v190, v57
	v_mul_f32_e32 v247, v247, v58
	v_mul_f32_e32 v191, v191, v59
	v_mul_f32_e32 v248, v248, v60
	v_mul_f32_e32 v192, v192, v61
	v_mul_f32_e32 v249, v249, v62
	v_mul_f32_e32 v193, v193, v63
	v_mul_f32_e32 v250, v250, v64
	v_mul_f32_e32 v194, v194, v65
	v_mul_f32_e32 v251, v251, v66
	v_mul_f32_e32 v195, v195, v67
	v_mul_f32_e32 v176, v176, v68
	v_mul_f32_e32 v196, v196, v69
	v_mul_f32_e32 v177, v177, v70
	v_mul_f32_e32 v197, v197, v71
	v_fmac_f32_e32 v238, v88, v246
	v_fmac_f32_e32 v198, v89, v190
	v_fmac_f32_e32 v239, v90, v247
	v_fmac_f32_e32 v199, v91, v191
	v_fmac_f32_e32 v240, v92, v248
	v_fmac_f32_e32 v200, v93, v192
	v_fmac_f32_e32 v241, v94, v249
	v_fmac_f32_e32 v201, v95, v193
	v_fmac_f32_e32 v242, v96, v250
	v_fmac_f32_e32 v202, v97, v194
	v_fmac_f32_e32 v243, v98, v251
	v_fmac_f32_e32 v203, v99, v195
	v_fmac_f32_e32 v244, v100, v176
	v_fmac_f32_e32 v204, v101, v196
	v_fmac_f32_e32 v245, v102, v177
	v_fmac_f32_e32 v205, v103, v197
	v_cvt_pk_bf16_f32 v120, v238, v198
	v_cvt_pk_bf16_f32 v121, v239, v199
	global_store_dwordx2 v4, v[120:121], s[4:5] offset:0 nt
	v_cvt_pk_bf16_f32 v122, v240, v200
	v_cvt_pk_bf16_f32 v123, v241, v201
	global_store_dwordx2 v4, v[122:123], s[4:5] offset:512 nt
	v_cvt_pk_bf16_f32 v124, v242, v202
	v_cvt_pk_bf16_f32 v125, v243, v203
	global_store_dwordx2 v4, v[124:125], s[4:5] offset:1024 nt
	v_cvt_pk_bf16_f32 v126, v244, v204
	v_cvt_pk_bf16_f32 v127, v245, v205
	global_store_dwordx2 v4, v[126:127], s[4:5] offset:1536 nt
	v_mul_f32_e32 v178, v238, v238
	v_fmac_f32_e32 v178, v198, v198
	v_fmac_f32_e32 v178, v239, v239
	v_fmac_f32_e32 v178, v199, v199
	v_fmac_f32_e32 v178, v240, v240
	v_fmac_f32_e32 v178, v200, v200
	v_fmac_f32_e32 v178, v241, v241
	v_fmac_f32_e32 v178, v201, v201
	v_fmac_f32_e32 v178, v242, v242
	v_fmac_f32_e32 v178, v202, v202
	v_fmac_f32_e32 v178, v243, v243
	v_fmac_f32_e32 v178, v203, v203
	v_fmac_f32_e32 v178, v244, v244
	v_fmac_f32_e32 v178, v204, v204
	v_fmac_f32_e32 v178, v245, v245
	v_fmac_f32_e32 v178, v205, v205
	s_nop 1
	v_add_f32_dpp v178, v178, v178 quad_perm:[1,0,3,2] row_mask:0xf bank_mask:0xf bound_ctrl:1
	s_nop 1
	v_add_f32_dpp v178, v178, v178 quad_perm:[2,3,0,1] row_mask:0xf bank_mask:0xf bound_ctrl:1
	s_nop 1
	v_add_f32_dpp v178, v178, v178 row_half_mirror row_mask:0xf bank_mask:0xf bound_ctrl:1
	s_nop 1
	v_add_f32_dpp v178, v178, v178 row_mirror row_mask:0xf bank_mask:0xf bound_ctrl:1
	s_nop 1
	v_add_f32_dpp v178, v178, v178 row_bcast:15 row_mask:0xa bank_mask:0xf
	s_nop 1
	v_add_f32_dpp v178, v178, v178 row_bcast:31 row_mask:0xc bank_mask:0xf
	s_nop 0
	v_readlane_b32 s0, v178, 63
	s_nop 1
	v_mov_b32_e32 v181, s0
	v_fmamk_f32 v181, v181, 0x3a800000, v161
	v_rsq_f32_e32 v180, v181
	s_nop 0
	v_mul_f32_e32 v238, v238, v180
	v_mul_f32_e32 v198, v198, v180
	v_mul_f32_e32 v239, v239, v180
	v_mul_f32_e32 v199, v199, v180
	v_mul_f32_e32 v240, v240, v180
	v_mul_f32_e32 v200, v200, v180
	v_mul_f32_e32 v241, v241, v180
	v_mul_f32_e32 v201, v201, v180
	v_mul_f32_e32 v242, v242, v180
	v_mul_f32_e32 v202, v202, v180
	v_mul_f32_e32 v243, v243, v180
	v_mul_f32_e32 v203, v203, v180
	v_mul_f32_e32 v244, v244, v180
	v_mul_f32_e32 v204, v204, v180
	v_mul_f32_e32 v245, v245, v180
	v_mul_f32_e32 v205, v205, v180
	v_mul_f32_e32 v238, v238, v72
	v_mul_f32_e32 v198, v198, v73
	v_mul_f32_e32 v239, v239, v74
	v_mul_f32_e32 v199, v199, v75
	v_mul_f32_e32 v240, v240, v76
	v_mul_f32_e32 v200, v200, v77
	v_mul_f32_e32 v241, v241, v78
	v_mul_f32_e32 v201, v201, v79
	v_mul_f32_e32 v242, v242, v80
	v_mul_f32_e32 v202, v202, v81
	v_mul_f32_e32 v243, v243, v82
	v_mul_f32_e32 v203, v203, v83
	v_mul_f32_e32 v244, v244, v84
	v_mul_f32_e32 v204, v204, v85
	v_mul_f32_e32 v245, v245, v86
	v_mul_f32_e32 v205, v205, v87
	v_fma_f32 v238, v238, v104, v134
	v_fma_f32 v198, v198, v105, v135
	v_fma_f32 v239, v239, v106, v136
	v_fma_f32 v199, v199, v107, v137
	v_fma_f32 v240, v240, v108, v138
	v_fma_f32 v200, v200, v109, v139
	v_fma_f32 v241, v241, v110, v140
	v_fma_f32 v201, v201, v111, v141
	v_fma_f32 v242, v242, v112, v142
	v_fma_f32 v202, v202, v113, v143
	v_fma_f32 v243, v243, v114, v144
	v_fma_f32 v203, v203, v115, v145
	v_fma_f32 v244, v244, v116, v146
	v_fma_f32 v204, v204, v117, v147
	v_fma_f32 v245, v245, v118, v148
	v_fma_f32 v205, v205, v119, v149
	v_cvt_pk_bf16_f32 v150, v238, v198
	v_cvt_pk_bf16_f32 v151, v239, v199
	global_store_dwordx2 v4, v[150:151], s[8:9] offset:0
	v_cvt_pk_bf16_f32 v152, v240, v200
	v_cvt_pk_bf16_f32 v153, v241, v201
	global_store_dwordx2 v4, v[152:153], s[8:9] offset:512
	v_cvt_pk_bf16_f32 v154, v242, v202
	v_cvt_pk_bf16_f32 v155, v243, v203
	global_store_dwordx2 v4, v[154:155], s[8:9] offset:1024
	v_cvt_pk_bf16_f32 v156, v244, v204
	v_cvt_pk_bf16_f32 v157, v245, v205
	global_store_dwordx2 v4, v[156:157], s[8:9] offset:1536
	s_mov_b64 s[0:1], 0
	s_branch .LBB0_190
